# residual GEMM epilogues (P4, P7): lane remap via ds_bpermute so 4 neighbouring lanes cover 64 contiguous bytes of a row, plus 3-row load pipeline with counted vmcnt
# speedup vs baseline: 1.0080x; 1.0052x over previous
;     __device__ __forceinline__ void operator()(const f32x4 (&acc)[2][2][4][2], const int upm, const int upn, const int usplit, int wr, int wc, int fr, int fq) const {
;         const int row0 = upm * BM + wr * 64 + fr, col0 = upn * BM + wc * 32 + 4 * fq;
;         if (usplit) {
;             float* sl = slab + ((size_t)(usplit - 1) * NCTX + (row0 - NLAT)) * DM + col0;
; #pragma unroll
;             for (int ai = 0; ai < 2; ++ai)
; #pragma unroll
;                 for (int m = 0; m < 4; ++m)
; #pragma unroll
;                     for (int bj = 0; bj < 2; ++bj)
; #pragma unroll
;                         for (int n = 0; n < 2; ++n) *(f32x4*)(sl + (size_t)(ai * HALF + m * 16) * DM + bj * HALF + n * 16) = acc[ai][bj][m][n];
;             return;
;         }
;         const bool lat = upm * BM < NLAT; const int b = lat ? ((upm * BM) >> 11) : 16;
;         const float* gp = gate + (size_t)b * 6144 + col0;
;         f32x4 gv[2][2];
; #pragma unroll
;         for (int bj = 0; bj < 2; ++bj)
; #pragma unroll
;             for (int n = 0; n < 2; ++n) gv[bj][n] = *(const f32x4*)(gp + bj * HALF + n * 16);
;         const float* sb = lat ? src_lat : src_ctx - (size_t)NLAT * DM; float* db = lat ? dst_lat : dst_ctx - (size_t)NLAT * DM;
; #pragma unroll
;         for (int ai = 0; ai < 2; ++ai)
; #pragma unroll
;             for (int mh = 0; mh < 2; ++mh) {
;                 f32x4 xv[2][2][2];
; #pragma unroll
;                 for (int m = 0; m < 2; ++m)
; #pragma unroll
;                     for (int bj = 0; bj < 2; ++bj)
; #pragma unroll
;                         for (int n = 0; n < 2; ++n) xv[m][bj][n] = *(const f32x4*)(sb + (size_t)(row0 + ai * HALF + (mh * 2 + m) * 16) * DM + col0 + bj * HALF + n * 16);
;                 __builtin_amdgcn_sched_barrier(0);
; #pragma unroll
;                 for (int m = 0; m < 2; ++m)
; #pragma unroll
;                     for (int bj = 0; bj < 2; ++bj)
; #pragma unroll
;                         for (int n = 0; n < 2; ++n) {
;                             const size_t o = (size_t)(row0 + ai * HALF + (mh * 2 + m) * 16) * DM + col0 + bj * HALF + n * 16;
;                             const f32x4 r = xv[m][bj][n] + gv[bj][n] * acc[ai][bj][mh * 2 + m][n];
;                             *(f32x4*)(db + o) = r;
;                             if (xb && lat) { u32x2 pk; pk.x = pk2(r[0], r[1]); pk.y = pk2(r[2], r[3]); *(u32x2*)(xb + o) = pk; }
.LBB0_1497:
	s_lshl_b64 s[30:31], s[90:91], 2
	s_add_u32 s30, s22, s30
	s_addc_u32 s31, s23, s31
	v_mbcnt_lo_u32_b32 v152, -1, 0
	v_mbcnt_hi_u32_b32 v152, -1, v152
	v_and_b32_e32 v153, 15, v152
	v_lshrrev_b32_e32 v154, 2, v152
	v_lshrrev_b32_e32 v155, 4, v152
	v_and_b32_e32 v156, 3, v152
	v_sub_u32_e32 v192, v192, v153
	v_add_u32_e32 v192, v192, v154
	v_ashrrev_i32_e32 v193, 31, v192
	v_sub_u32_e32 v157, v156, v155
	v_lshl_add_u32 v190, v157, 2, v190
	v_ashrrev_i32_e32 v191, 31, v190
	v_lshl_add_u32 v158, v156, 4, v154
	v_lshlrev_b64 v[198:199], 2, v[190:191]
	v_lshl_add_u64 v[242:243], s[30:31], 0, v[198:199]
	v_lshl_add_u64 v[200:201], s[74:75], 0, v[198:199]
	v_lshl_add_u64 v[218:219], s[68:69], 0, v[198:199]
	v_lshlrev_b64 v[198:199], 12, v[192:193]
	v_lshl_add_u64 v[200:201], v[200:201], 0, v[198:199]
	v_lshl_add_u64 v[218:219], v[218:219], 0, v[198:199]
	global_load_dwordx4 v[148:151], v[242:243], off
	global_load_dwordx4 v[144:147], v[242:243], off offset:64
	global_load_dwordx4 v[140:143], v[242:243], off offset:512
	global_load_dwordx4 v[136:139], v[242:243], off offset:576
	v_lshlrev_b64 v[198:199], 1, v[190:191]
	v_lshl_add_u64 v[242:243], s[44:45], 0, v[198:199]
	v_lshlrev_b64 v[198:199], 11, v[192:193]
	v_lshl_add_u64 v[242:243], v[242:243], 0, v[198:199]
	v_lshlrev_b32_e32 v198, 2, v158
	global_load_dwordx4 v[152:155], v[200:201], off
	global_load_dwordx4 v[156:159], v[200:201], off offset:64
	global_load_dwordx4 v[160:163], v[200:201], off offset:512
	global_load_dwordx4 v[164:167], v[200:201], off offset:576
	s_mov_b32 s30, 0x10000
	s_mov_b32 s31, 0
	v_lshl_add_u64 v[200:201], v[200:201], 0, s[30:31]
	global_load_dwordx4 v[168:171], v[200:201], off
	global_load_dwordx4 v[172:175], v[200:201], off offset:64
	global_load_dwordx4 v[176:179], v[200:201], off offset:512
	global_load_dwordx4 v[180:183], v[200:201], off offset:576
	s_mov_b32 s30, 0x10000
	s_mov_b32 s31, 0
	v_lshl_add_u64 v[200:201], v[200:201], 0, s[30:31]
	global_load_dwordx4 v[190:193], v[200:201], off
	global_load_dwordx4 v[194:197], v[200:201], off offset:64
	global_load_dwordx4 v[234:237], v[200:201], off offset:512
	global_load_dwordx4 v[238:241], v[200:201], off offset:576
	s_mov_b32 s30, 0x10000
	s_mov_b32 s31, 0
	v_lshl_add_u64 v[200:201], v[200:201], 0, s[30:31]
	s_and_b64 s[30:31], s[58:59], s[72:73]
	s_xor_b64 s[66:67], s[30:31], -1
	s_and_b64 vcc, exec, s[66:67]
	s_cbranch_vccnz .Lmy_epi_p4_nobf
	ds_bpermute_b32 v132, v198, v132
	ds_bpermute_b32 v133, v198, v133
	ds_bpermute_b32 v134, v198, v134
	ds_bpermute_b32 v135, v198, v135
	ds_bpermute_b32 v128, v198, v128
	ds_bpermute_b32 v129, v198, v129
	ds_bpermute_b32 v130, v198, v130
	ds_bpermute_b32 v131, v198, v131
	ds_bpermute_b32 v124, v198, v124
	ds_bpermute_b32 v125, v198, v125
	ds_bpermute_b32 v126, v198, v126
	ds_bpermute_b32 v127, v198, v127
	ds_bpermute_b32 v120, v198, v120
	ds_bpermute_b32 v121, v198, v121
	ds_bpermute_b32 v122, v198, v122
	ds_bpermute_b32 v123, v198, v123
	s_waitcnt vmcnt(8)
	s_waitcnt lgkmcnt(0)
	v_pk_fma_f32 v[152:153], v[132:133], v[148:149], v[152:153]
	v_pk_fma_f32 v[154:155], v[134:135], v[150:151], v[154:155]
	v_pk_fma_f32 v[156:157], v[128:129], v[144:145], v[156:157]
	v_pk_fma_f32 v[158:159], v[130:131], v[146:147], v[158:159]
	v_pk_fma_f32 v[160:161], v[124:125], v[140:141], v[160:161]
	v_pk_fma_f32 v[162:163], v[126:127], v[142:143], v[162:163]
	v_pk_fma_f32 v[164:165], v[120:121], v[136:137], v[164:165]
	v_pk_fma_f32 v[166:167], v[122:123], v[138:139], v[166:167]
	global_store_dwordx4 v[218:219], v[152:155], off
	global_store_dwordx4 v[218:219], v[156:159], off offset:64
	global_store_dwordx4 v[218:219], v[160:163], off offset:512
	global_store_dwordx4 v[218:219], v[164:167], off offset:576
	v_cvt_pk_bf16_f32 v132, v152, v153
	v_cvt_pk_bf16_f32 v133, v154, v155
	v_cvt_pk_bf16_f32 v128, v156, v157
	v_cvt_pk_bf16_f32 v129, v158, v159
	v_cvt_pk_bf16_f32 v124, v160, v161
	v_cvt_pk_bf16_f32 v125, v162, v163
	v_cvt_pk_bf16_f32 v120, v164, v165
	v_cvt_pk_bf16_f32 v121, v166, v167
	global_store_dwordx2 v[242:243], v[132:133], off
	global_store_dwordx2 v[242:243], v[128:129], off offset:32
	global_store_dwordx2 v[242:243], v[124:125], off offset:256
	global_store_dwordx2 v[242:243], v[120:121], off offset:288
	s_mov_b32 s30, 0x10000
	s_mov_b32 s31, 0
	v_lshl_add_u64 v[218:219], v[218:219], 0, s[30:31]
	s_mov_b32 s30, 0x8000
	s_mov_b32 s31, 0
	v_lshl_add_u64 v[242:243], v[242:243], 0, s[30:31]
	global_load_dwordx4 v[152:155], v[200:201], off
	global_load_dwordx4 v[156:159], v[200:201], off offset:64
	global_load_dwordx4 v[160:163], v[200:201], off offset:512
	global_load_dwordx4 v[164:167], v[200:201], off offset:576
	s_mov_b32 s30, 0x50000
	s_mov_b32 s31, 0
	v_lshl_add_u64 v[200:201], v[200:201], 0, s[30:31]
	global_load_dwordx4 v[132:135], v[200:201], off
	global_load_dwordx4 v[128:131], v[200:201], off offset:64
	global_load_dwordx4 v[124:127], v[200:201], off offset:512
	global_load_dwordx4 v[120:123], v[200:201], off offset:576
	s_mov_b32 s30, 0x10000
	s_mov_b32 s31, 0
	v_lshl_add_u64 v[200:201], v[200:201], 0, s[30:31]
	ds_bpermute_b32 v116, v198, v116
	ds_bpermute_b32 v117, v198, v117
	ds_bpermute_b32 v118, v198, v118
	ds_bpermute_b32 v119, v198, v119
	ds_bpermute_b32 v112, v198, v112
	ds_bpermute_b32 v113, v198, v113
	ds_bpermute_b32 v114, v198, v114
	ds_bpermute_b32 v115, v198, v115
	ds_bpermute_b32 v108, v198, v108
	ds_bpermute_b32 v109, v198, v109
	ds_bpermute_b32 v110, v198, v110
	ds_bpermute_b32 v111, v198, v111
	ds_bpermute_b32 v104, v198, v104
	ds_bpermute_b32 v105, v198, v105
	ds_bpermute_b32 v106, v198, v106
	ds_bpermute_b32 v107, v198, v107
	s_waitcnt vmcnt(20)
; __device__ __forceinline__ unsigned pk2(float lo, float hi) { const f32v2_t f = {lo, hi}; const bf16v2_t b = __builtin_convertvector(f, bf16v2_t); return __builtin_bit_cast(unsigned, b); }
;     __device__ __forceinline__ void operator()(const f32x4 (&acc)[2][2][4][2], const int upm, const int upn, const int usplit, int wr, int wc, int fr, int fq) const {
;     ...
;         const bool lat = upm * BM < NLAT; const int b = lat ? ((upm * BM) >> 11) : 16;
;         const float* gp = gate + (size_t)b * 6144 + col0;
;         f32x4 gv[2][2];
; #pragma unroll
;         for (int bj = 0; bj < 2; ++bj)
; #pragma unroll
;             for (int n = 0; n < 2; ++n) gv[bj][n] = *(const f32x4*)(gp + bj * HALF + n * 16);
;         const float* sb = lat ? src_lat : src_ctx - (size_t)NLAT * DM; float* db = lat ? dst_lat : dst_ctx - (size_t)NLAT * DM;
; #pragma unroll
;         for (int ai = 0; ai < 2; ++ai)
; #pragma unroll
;             for (int mh = 0; mh < 2; ++mh) {
;                 f32x4 xv[2][2][2];
; #pragma unroll
;                 for (int m = 0; m < 2; ++m)
; #pragma unroll
;                     for (int bj = 0; bj < 2; ++bj)
; #pragma unroll
;                         for (int n = 0; n < 2; ++n) xv[m][bj][n] = *(const f32x4*)(sb + (size_t)(row0 + ai * HALF + (mh * 2 + m) * 16) * DM + col0 + bj * HALF + n * 16);
;                 __builtin_amdgcn_sched_barrier(0);
; #pragma unroll
;                 for (int m = 0; m < 2; ++m)
; #pragma unroll
;                     for (int bj = 0; bj < 2; ++bj)
; #pragma unroll
;                         for (int n = 0; n < 2; ++n) {
;                             const size_t o = (size_t)(row0 + ai * HALF + (mh * 2 + m) * 16) * DM + col0 + bj * HALF + n * 16;
;                             const f32x4 r = xv[m][bj][n] + gv[bj][n] * acc[ai][bj][mh * 2 + m][n];
;                             *(f32x4*)(db + o) = r;
;                             if (xb && lat) { u32x2 pk; pk.x = pk2(r[0], r[1]); pk.y = pk2(r[2], r[3]); *(u32x2*)(xb + o) = pk; }
;                         }
	s_waitcnt lgkmcnt(0)
	v_pk_fma_f32 v[168:169], v[116:117], v[148:149], v[168:169]
	v_pk_fma_f32 v[170:171], v[118:119], v[150:151], v[170:171]
	v_pk_fma_f32 v[172:173], v[112:113], v[144:145], v[172:173]
	v_pk_fma_f32 v[174:175], v[114:115], v[146:147], v[174:175]
	v_pk_fma_f32 v[176:177], v[108:109], v[140:141], v[176:177]
	v_pk_fma_f32 v[178:179], v[110:111], v[142:143], v[178:179]
	v_pk_fma_f32 v[180:181], v[104:105], v[136:137], v[180:181]
	v_pk_fma_f32 v[182:183], v[106:107], v[138:139], v[182:183]
	global_store_dwordx4 v[218:219], v[168:171], off
	global_store_dwordx4 v[218:219], v[172:175], off offset:64
	global_store_dwordx4 v[218:219], v[176:179], off offset:512
	global_store_dwordx4 v[218:219], v[180:183], off offset:576
	v_cvt_pk_bf16_f32 v116, v168, v169
	v_cvt_pk_bf16_f32 v117, v170, v171
	v_cvt_pk_bf16_f32 v112, v172, v173
	v_cvt_pk_bf16_f32 v113, v174, v175
	v_cvt_pk_bf16_f32 v108, v176, v177
	v_cvt_pk_bf16_f32 v109, v178, v179
	v_cvt_pk_bf16_f32 v104, v180, v181
	v_cvt_pk_bf16_f32 v105, v182, v183
	global_store_dwordx2 v[242:243], v[116:117], off
	global_store_dwordx2 v[242:243], v[112:113], off offset:32
	global_store_dwordx2 v[242:243], v[108:109], off offset:256
	global_store_dwordx2 v[242:243], v[104:105], off offset:288
	s_mov_b32 s30, 0x10000
	s_mov_b32 s31, 0
	v_lshl_add_u64 v[218:219], v[218:219], 0, s[30:31]
	s_mov_b32 s30, 0x8000
	s_mov_b32 s31, 0
	v_lshl_add_u64 v[242:243], v[242:243], 0, s[30:31]
	global_load_dwordx4 v[168:171], v[200:201], off
	global_load_dwordx4 v[172:175], v[200:201], off offset:64
	global_load_dwordx4 v[176:179], v[200:201], off offset:512
	global_load_dwordx4 v[180:183], v[200:201], off offset:576
	s_mov_b32 s30, 0x10000
	s_mov_b32 s31, 0
	v_lshl_add_u64 v[200:201], v[200:201], 0, s[30:31]
	global_load_dwordx4 v[116:119], v[200:201], off
	global_load_dwordx4 v[112:115], v[200:201], off offset:64
	global_load_dwordx4 v[108:111], v[200:201], off offset:512
	global_load_dwordx4 v[104:107], v[200:201], off offset:576
	s_mov_b32 s30, 0x10000
	s_mov_b32 s31, 0
	v_lshl_add_u64 v[200:201], v[200:201], 0, s[30:31]
	ds_bpermute_b32 v100, v198, v100
	ds_bpermute_b32 v101, v198, v101
	ds_bpermute_b32 v102, v198, v102
	ds_bpermute_b32 v103, v198, v103
	ds_bpermute_b32 v96, v198, v96
	ds_bpermute_b32 v97, v198, v97
	ds_bpermute_b32 v98, v198, v98
	ds_bpermute_b32 v99, v198, v99
	ds_bpermute_b32 v92, v198, v92
	ds_bpermute_b32 v93, v198, v93
	ds_bpermute_b32 v94, v198, v94
	ds_bpermute_b32 v95, v198, v95
	ds_bpermute_b32 v88, v198, v88
	ds_bpermute_b32 v89, v198, v89
	ds_bpermute_b32 v90, v198, v90
	ds_bpermute_b32 v91, v198, v91
	s_waitcnt vmcnt(32)
	s_waitcnt lgkmcnt(0)
	v_pk_fma_f32 v[190:191], v[100:101], v[148:149], v[190:191]
	v_pk_fma_f32 v[192:193], v[102:103], v[150:151], v[192:193]
	v_pk_fma_f32 v[194:195], v[96:97], v[144:145], v[194:195]
	v_pk_fma_f32 v[196:197], v[98:99], v[146:147], v[196:197]
	v_pk_fma_f32 v[234:235], v[92:93], v[140:141], v[234:235]
	v_pk_fma_f32 v[236:237], v[94:95], v[142:143], v[236:237]
	v_pk_fma_f32 v[238:239], v[88:89], v[136:137], v[238:239]
	v_pk_fma_f32 v[240:241], v[90:91], v[138:139], v[240:241]
	global_store_dwordx4 v[218:219], v[190:193], off
	global_store_dwordx4 v[218:219], v[194:197], off offset:64
	global_store_dwordx4 v[218:219], v[234:237], off offset:512
	global_store_dwordx4 v[218:219], v[238:241], off offset:576
	v_cvt_pk_bf16_f32 v100, v190, v191
	v_cvt_pk_bf16_f32 v101, v192, v193
	v_cvt_pk_bf16_f32 v96, v194, v195
	v_cvt_pk_bf16_f32 v97, v196, v197
	v_cvt_pk_bf16_f32 v92, v234, v235
	v_cvt_pk_bf16_f32 v93, v236, v237
	v_cvt_pk_bf16_f32 v88, v238, v239
	v_cvt_pk_bf16_f32 v89, v240, v241
	global_store_dwordx2 v[242:243], v[100:101], off
	global_store_dwordx2 v[242:243], v[96:97], off offset:32
	global_store_dwordx2 v[242:243], v[92:93], off offset:256
	global_store_dwordx2 v[242:243], v[88:89], off offset:288
	s_mov_b32 s30, 0x10000
	s_mov_b32 s31, 0
	v_lshl_add_u64 v[218:219], v[218:219], 0, s[30:31]
	s_mov_b32 s30, 0x8000
	s_mov_b32 s31, 0
	v_lshl_add_u64 v[242:243], v[242:243], 0, s[30:31]
	global_load_dwordx4 v[190:193], v[200:201], off
	global_load_dwordx4 v[194:197], v[200:201], off offset:64
	global_load_dwordx4 v[234:237], v[200:201], off offset:512
	global_load_dwordx4 v[238:241], v[200:201], off offset:576
	ds_bpermute_b32 v84, v198, v84
	ds_bpermute_b32 v85, v198, v85
	ds_bpermute_b32 v86, v198, v86
	ds_bpermute_b32 v87, v198, v87
	ds_bpermute_b32 v80, v198, v80
	ds_bpermute_b32 v81, v198, v81
	ds_bpermute_b32 v82, v198, v82
	ds_bpermute_b32 v83, v198, v83
	ds_bpermute_b32 v76, v198, v76
	ds_bpermute_b32 v77, v198, v77
	ds_bpermute_b32 v78, v198, v78
	ds_bpermute_b32 v79, v198, v79
	ds_bpermute_b32 v72, v198, v72
	ds_bpermute_b32 v73, v198, v73
	ds_bpermute_b32 v74, v198, v74
	ds_bpermute_b32 v75, v198, v75
	s_waitcnt vmcnt(32)
	s_waitcnt lgkmcnt(0)
; __device__ __forceinline__ unsigned pk2(float lo, float hi) { const f32v2_t f = {lo, hi}; const bf16v2_t b = __builtin_convertvector(f, bf16v2_t); return __builtin_bit_cast(unsigned, b); }
;     __device__ __forceinline__ void operator()(const f32x4 (&acc)[2][2][4][2], const int upm, const int upn, const int usplit, int wr, int wc, int fr, int fq) const {
;     ...
;         const bool lat = upm * BM < NLAT; const int b = lat ? ((upm * BM) >> 11) : 16;
;         const float* gp = gate + (size_t)b * 6144 + col0;
;         f32x4 gv[2][2];
; #pragma unroll
;         for (int bj = 0; bj < 2; ++bj)
; #pragma unroll
;             for (int n = 0; n < 2; ++n) gv[bj][n] = *(const f32x4*)(gp + bj * HALF + n * 16);
;         const float* sb = lat ? src_lat : src_ctx - (size_t)NLAT * DM; float* db = lat ? dst_lat : dst_ctx - (size_t)NLAT * DM;
; #pragma unroll
;         for (int ai = 0; ai < 2; ++ai)
; #pragma unroll
;             for (int mh = 0; mh < 2; ++mh) {
;                 f32x4 xv[2][2][2];
; #pragma unroll
;                 for (int m = 0; m < 2; ++m)
; #pragma unroll
;                     for (int bj = 0; bj < 2; ++bj)
; #pragma unroll
;                         for (int n = 0; n < 2; ++n) xv[m][bj][n] = *(const f32x4*)(sb + (size_t)(row0 + ai * HALF + (mh * 2 + m) * 16) * DM + col0 + bj * HALF + n * 16);
;                 __builtin_amdgcn_sched_barrier(0);
; #pragma unroll
;                 for (int m = 0; m < 2; ++m)
; #pragma unroll
;                     for (int bj = 0; bj < 2; ++bj)
; #pragma unroll
;                         for (int n = 0; n < 2; ++n) {
;                             const size_t o = (size_t)(row0 + ai * HALF + (mh * 2 + m) * 16) * DM + col0 + bj * HALF + n * 16;
;                             const f32x4 r = xv[m][bj][n] + gv[bj][n] * acc[ai][bj][mh * 2 + m][n];
;                             *(f32x4*)(db + o) = r;
;                             if (xb && lat) { u32x2 pk; pk.x = pk2(r[0], r[1]); pk.y = pk2(r[2], r[3]); *(u32x2*)(xb + o) = pk; }
;                         }
	v_pk_fma_f32 v[152:153], v[84:85], v[148:149], v[152:153]
	v_pk_fma_f32 v[154:155], v[86:87], v[150:151], v[154:155]
	v_pk_fma_f32 v[156:157], v[80:81], v[144:145], v[156:157]
	v_pk_fma_f32 v[158:159], v[82:83], v[146:147], v[158:159]
	v_pk_fma_f32 v[160:161], v[76:77], v[140:141], v[160:161]
	v_pk_fma_f32 v[162:163], v[78:79], v[142:143], v[162:163]
	v_pk_fma_f32 v[164:165], v[72:73], v[136:137], v[164:165]
	v_pk_fma_f32 v[166:167], v[74:75], v[138:139], v[166:167]
	global_store_dwordx4 v[218:219], v[152:155], off
	global_store_dwordx4 v[218:219], v[156:159], off offset:64
	global_store_dwordx4 v[218:219], v[160:163], off offset:512
	global_store_dwordx4 v[218:219], v[164:167], off offset:576
	v_cvt_pk_bf16_f32 v84, v152, v153
	v_cvt_pk_bf16_f32 v85, v154, v155
	v_cvt_pk_bf16_f32 v80, v156, v157
	v_cvt_pk_bf16_f32 v81, v158, v159
	v_cvt_pk_bf16_f32 v76, v160, v161
	v_cvt_pk_bf16_f32 v77, v162, v163
	v_cvt_pk_bf16_f32 v72, v164, v165
	v_cvt_pk_bf16_f32 v73, v166, v167
	global_store_dwordx2 v[242:243], v[84:85], off
	global_store_dwordx2 v[242:243], v[80:81], off offset:32
	global_store_dwordx2 v[242:243], v[76:77], off offset:256
	global_store_dwordx2 v[242:243], v[72:73], off offset:288
	s_mov_b32 s30, 0x50000
	s_mov_b32 s31, 0
	v_lshl_add_u64 v[218:219], v[218:219], 0, s[30:31]
	s_mov_b32 s30, 0x28000
	s_mov_b32 s31, 0
	v_lshl_add_u64 v[242:243], v[242:243], 0, s[30:31]
	ds_bpermute_b32 v68, v198, v68
	ds_bpermute_b32 v69, v198, v69
	ds_bpermute_b32 v70, v198, v70
	ds_bpermute_b32 v71, v198, v71
	ds_bpermute_b32 v64, v198, v64
	ds_bpermute_b32 v65, v198, v65
	ds_bpermute_b32 v66, v198, v66
	ds_bpermute_b32 v67, v198, v67
	ds_bpermute_b32 v60, v198, v60
	ds_bpermute_b32 v61, v198, v61
	ds_bpermute_b32 v62, v198, v62
	ds_bpermute_b32 v63, v198, v63
	ds_bpermute_b32 v56, v198, v56
	ds_bpermute_b32 v57, v198, v57
	ds_bpermute_b32 v58, v198, v58
	ds_bpermute_b32 v59, v198, v59
	s_waitcnt vmcnt(36)
	s_waitcnt lgkmcnt(0)
	v_pk_fma_f32 v[132:133], v[68:69], v[148:149], v[132:133]
	v_pk_fma_f32 v[134:135], v[70:71], v[150:151], v[134:135]
	v_pk_fma_f32 v[128:129], v[64:65], v[144:145], v[128:129]
	v_pk_fma_f32 v[130:131], v[66:67], v[146:147], v[130:131]
	v_pk_fma_f32 v[124:125], v[60:61], v[140:141], v[124:125]
	v_pk_fma_f32 v[126:127], v[62:63], v[142:143], v[126:127]
	v_pk_fma_f32 v[120:121], v[56:57], v[136:137], v[120:121]
	v_pk_fma_f32 v[122:123], v[58:59], v[138:139], v[122:123]
	global_store_dwordx4 v[218:219], v[132:135], off
	global_store_dwordx4 v[218:219], v[128:131], off offset:64
	global_store_dwordx4 v[218:219], v[124:127], off offset:512
	global_store_dwordx4 v[218:219], v[120:123], off offset:576
	v_cvt_pk_bf16_f32 v68, v132, v133
	v_cvt_pk_bf16_f32 v69, v134, v135
	v_cvt_pk_bf16_f32 v64, v128, v129
	v_cvt_pk_bf16_f32 v65, v130, v131
	v_cvt_pk_bf16_f32 v60, v124, v125
	v_cvt_pk_bf16_f32 v61, v126, v127
	v_cvt_pk_bf16_f32 v56, v120, v121
	v_cvt_pk_bf16_f32 v57, v122, v123
	global_store_dwordx2 v[242:243], v[68:69], off
	global_store_dwordx2 v[242:243], v[64:65], off offset:32
	global_store_dwordx2 v[242:243], v[60:61], off offset:256
	global_store_dwordx2 v[242:243], v[56:57], off offset:288
	s_mov_b32 s30, 0x10000
	s_mov_b32 s31, 0
	v_lshl_add_u64 v[218:219], v[218:219], 0, s[30:31]
	s_mov_b32 s30, 0x8000
	s_mov_b32 s31, 0
	v_lshl_add_u64 v[242:243], v[242:243], 0, s[30:31]
	ds_bpermute_b32 v52, v198, v52
	ds_bpermute_b32 v53, v198, v53
	ds_bpermute_b32 v54, v198, v54
	ds_bpermute_b32 v55, v198, v55
	ds_bpermute_b32 v48, v198, v48
	ds_bpermute_b32 v49, v198, v49
	ds_bpermute_b32 v50, v198, v50
	ds_bpermute_b32 v51, v198, v51
	ds_bpermute_b32 v44, v198, v44
	ds_bpermute_b32 v45, v198, v45
	ds_bpermute_b32 v46, v198, v46
	ds_bpermute_b32 v47, v198, v47
	ds_bpermute_b32 v40, v198, v40
	ds_bpermute_b32 v41, v198, v41
	ds_bpermute_b32 v42, v198, v42
	ds_bpermute_b32 v43, v198, v43
	s_waitcnt vmcnt(32)
	s_waitcnt lgkmcnt(0)
	v_pk_fma_f32 v[168:169], v[52:53], v[148:149], v[168:169]
	v_pk_fma_f32 v[170:171], v[54:55], v[150:151], v[170:171]
	v_pk_fma_f32 v[172:173], v[48:49], v[144:145], v[172:173]
	v_pk_fma_f32 v[174:175], v[50:51], v[146:147], v[174:175]
	v_pk_fma_f32 v[176:177], v[44:45], v[140:141], v[176:177]
	v_pk_fma_f32 v[178:179], v[46:47], v[142:143], v[178:179]
	v_pk_fma_f32 v[180:181], v[40:41], v[136:137], v[180:181]
	v_pk_fma_f32 v[182:183], v[42:43], v[138:139], v[182:183]
	global_store_dwordx4 v[218:219], v[168:171], off
	global_store_dwordx4 v[218:219], v[172:175], off offset:64
	global_store_dwordx4 v[218:219], v[176:179], off offset:512
	global_store_dwordx4 v[218:219], v[180:183], off offset:576
	v_cvt_pk_bf16_f32 v52, v168, v169
	v_cvt_pk_bf16_f32 v53, v170, v171
	v_cvt_pk_bf16_f32 v48, v172, v173
	v_cvt_pk_bf16_f32 v49, v174, v175
	v_cvt_pk_bf16_f32 v44, v176, v177
	v_cvt_pk_bf16_f32 v45, v178, v179
	v_cvt_pk_bf16_f32 v40, v180, v181
	v_cvt_pk_bf16_f32 v41, v182, v183
	global_store_dwordx2 v[242:243], v[52:53], off
	global_store_dwordx2 v[242:243], v[48:49], off offset:32
	global_store_dwordx2 v[242:243], v[44:45], off offset:256
	global_store_dwordx2 v[242:243], v[40:41], off offset:288
	s_mov_b32 s30, 0x10000
	s_mov_b32 s31, 0
	v_lshl_add_u64 v[218:219], v[218:219], 0, s[30:31]
	s_mov_b32 s30, 0x8000
	s_mov_b32 s31, 0
	v_lshl_add_u64 v[242:243], v[242:243], 0, s[30:31]
	ds_bpermute_b32 v36, v198, v36
	ds_bpermute_b32 v37, v198, v37
	ds_bpermute_b32 v38, v198, v38
	ds_bpermute_b32 v39, v198, v39
	ds_bpermute_b32 v32, v198, v32
	ds_bpermute_b32 v33, v198, v33
	ds_bpermute_b32 v34, v198, v34
	ds_bpermute_b32 v35, v198, v35
	ds_bpermute_b32 v28, v198, v28
	ds_bpermute_b32 v29, v198, v29
	ds_bpermute_b32 v30, v198, v30
	ds_bpermute_b32 v31, v198, v31
	ds_bpermute_b32 v24, v198, v24
	ds_bpermute_b32 v25, v198, v25
	ds_bpermute_b32 v26, v198, v26
	ds_bpermute_b32 v27, v198, v27
	s_waitcnt vmcnt(36)
; __device__ __forceinline__ unsigned pk2(float lo, float hi) { const f32v2_t f = {lo, hi}; const bf16v2_t b = __builtin_convertvector(f, bf16v2_t); return __builtin_bit_cast(unsigned, b); }
;     __device__ __forceinline__ void operator()(const f32x4 (&acc)[2][2][4][2], const int upm, const int upn, const int usplit, int wr, int wc, int fr, int fq) const {
;     ...
;         const bool lat = upm * BM < NLAT; const int b = lat ? ((upm * BM) >> 11) : 16;
;         const float* gp = gate + (size_t)b * 6144 + col0;
;         f32x4 gv[2][2];
; #pragma unroll
;         for (int bj = 0; bj < 2; ++bj)
; #pragma unroll
;             for (int n = 0; n < 2; ++n) gv[bj][n] = *(const f32x4*)(gp + bj * HALF + n * 16);
;         const float* sb = lat ? src_lat : src_ctx - (size_t)NLAT * DM; float* db = lat ? dst_lat : dst_ctx - (size_t)NLAT * DM;
; #pragma unroll
;         for (int ai = 0; ai < 2; ++ai)
; #pragma unroll
;             for (int mh = 0; mh < 2; ++mh) {
;                 f32x4 xv[2][2][2];
; #pragma unroll
;                 for (int m = 0; m < 2; ++m)
; #pragma unroll
;                     for (int bj = 0; bj < 2; ++bj)
; #pragma unroll
;                         for (int n = 0; n < 2; ++n) xv[m][bj][n] = *(const f32x4*)(sb + (size_t)(row0 + ai * HALF + (mh * 2 + m) * 16) * DM + col0 + bj * HALF + n * 16);
;                 __builtin_amdgcn_sched_barrier(0);
; #pragma unroll
;                 for (int m = 0; m < 2; ++m)
; #pragma unroll
;                     for (int bj = 0; bj < 2; ++bj)
; #pragma unroll
;                         for (int n = 0; n < 2; ++n) {
;                             const size_t o = (size_t)(row0 + ai * HALF + (mh * 2 + m) * 16) * DM + col0 + bj * HALF + n * 16;
;                             const f32x4 r = xv[m][bj][n] + gv[bj][n] * acc[ai][bj][mh * 2 + m][n];
;                             *(f32x4*)(db + o) = r;
;                             if (xb && lat) { u32x2 pk; pk.x = pk2(r[0], r[1]); pk.y = pk2(r[2], r[3]); *(u32x2*)(xb + o) = pk; }
;                         }
	s_waitcnt lgkmcnt(0)
	v_pk_fma_f32 v[116:117], v[36:37], v[148:149], v[116:117]
	v_pk_fma_f32 v[118:119], v[38:39], v[150:151], v[118:119]
	v_pk_fma_f32 v[112:113], v[32:33], v[144:145], v[112:113]
	v_pk_fma_f32 v[114:115], v[34:35], v[146:147], v[114:115]
	v_pk_fma_f32 v[108:109], v[28:29], v[140:141], v[108:109]
	v_pk_fma_f32 v[110:111], v[30:31], v[142:143], v[110:111]
	v_pk_fma_f32 v[104:105], v[24:25], v[136:137], v[104:105]
	v_pk_fma_f32 v[106:107], v[26:27], v[138:139], v[106:107]
	global_store_dwordx4 v[218:219], v[116:119], off
	global_store_dwordx4 v[218:219], v[112:115], off offset:64
	global_store_dwordx4 v[218:219], v[108:111], off offset:512
	global_store_dwordx4 v[218:219], v[104:107], off offset:576
	v_cvt_pk_bf16_f32 v36, v116, v117
	v_cvt_pk_bf16_f32 v37, v118, v119
	v_cvt_pk_bf16_f32 v32, v112, v113
	v_cvt_pk_bf16_f32 v33, v114, v115
	v_cvt_pk_bf16_f32 v28, v108, v109
	v_cvt_pk_bf16_f32 v29, v110, v111
	v_cvt_pk_bf16_f32 v24, v104, v105
	v_cvt_pk_bf16_f32 v25, v106, v107
	global_store_dwordx2 v[242:243], v[36:37], off
	global_store_dwordx2 v[242:243], v[32:33], off offset:32
	global_store_dwordx2 v[242:243], v[28:29], off offset:256
	global_store_dwordx2 v[242:243], v[24:25], off offset:288
	s_mov_b32 s30, 0x10000
	s_mov_b32 s31, 0
	v_lshl_add_u64 v[218:219], v[218:219], 0, s[30:31]
	s_mov_b32 s30, 0x8000
	s_mov_b32 s31, 0
	v_lshl_add_u64 v[242:243], v[242:243], 0, s[30:31]
	ds_bpermute_b32 v20, v198, v20
	ds_bpermute_b32 v21, v198, v21
	ds_bpermute_b32 v22, v198, v22
	ds_bpermute_b32 v23, v198, v23
	ds_bpermute_b32 v16, v198, v16
	ds_bpermute_b32 v17, v198, v17
	ds_bpermute_b32 v18, v198, v18
	ds_bpermute_b32 v19, v198, v19
	ds_bpermute_b32 v12, v198, v12
	ds_bpermute_b32 v13, v198, v13
	ds_bpermute_b32 v14, v198, v14
	ds_bpermute_b32 v15, v198, v15
	ds_bpermute_b32 v8, v198, v8
	ds_bpermute_b32 v9, v198, v9
	ds_bpermute_b32 v10, v198, v10
	ds_bpermute_b32 v11, v198, v11
	s_waitcnt vmcnt(32)
	s_waitcnt lgkmcnt(0)
	v_pk_fma_f32 v[190:191], v[20:21], v[148:149], v[190:191]
	v_pk_fma_f32 v[192:193], v[22:23], v[150:151], v[192:193]
	v_pk_fma_f32 v[194:195], v[16:17], v[144:145], v[194:195]
	v_pk_fma_f32 v[196:197], v[18:19], v[146:147], v[196:197]
	v_pk_fma_f32 v[234:235], v[12:13], v[140:141], v[234:235]
	v_pk_fma_f32 v[236:237], v[14:15], v[142:143], v[236:237]
	v_pk_fma_f32 v[238:239], v[8:9], v[136:137], v[238:239]
	v_pk_fma_f32 v[240:241], v[10:11], v[138:139], v[240:241]
	global_store_dwordx4 v[218:219], v[190:193], off
	global_store_dwordx4 v[218:219], v[194:197], off offset:64
	global_store_dwordx4 v[218:219], v[234:237], off offset:512
	global_store_dwordx4 v[218:219], v[238:241], off offset:576
	v_cvt_pk_bf16_f32 v20, v190, v191
	v_cvt_pk_bf16_f32 v21, v192, v193
	v_cvt_pk_bf16_f32 v16, v194, v195
	v_cvt_pk_bf16_f32 v17, v196, v197
	v_cvt_pk_bf16_f32 v12, v234, v235
	v_cvt_pk_bf16_f32 v13, v236, v237
	v_cvt_pk_bf16_f32 v8, v238, v239
	v_cvt_pk_bf16_f32 v9, v240, v241
	global_store_dwordx2 v[242:243], v[20:21], off
	global_store_dwordx2 v[242:243], v[16:17], off offset:32
	global_store_dwordx2 v[242:243], v[12:13], off offset:256
	global_store_dwordx2 v[242:243], v[8:9], off offset:288
	s_branch .LBB0_1481
.Lmy_epi_p4_nobf:
	ds_bpermute_b32 v132, v198, v132
	ds_bpermute_b32 v133, v198, v133
	ds_bpermute_b32 v134, v198, v134
	ds_bpermute_b32 v135, v198, v135
	ds_bpermute_b32 v128, v198, v128
	ds_bpermute_b32 v129, v198, v129
	ds_bpermute_b32 v130, v198, v130
	ds_bpermute_b32 v131, v198, v131
	ds_bpermute_b32 v124, v198, v124
	ds_bpermute_b32 v125, v198, v125
	ds_bpermute_b32 v126, v198, v126
	ds_bpermute_b32 v127, v198, v127
	ds_bpermute_b32 v120, v198, v120
	ds_bpermute_b32 v121, v198, v121
	ds_bpermute_b32 v122, v198, v122
	ds_bpermute_b32 v123, v198, v123
	s_waitcnt vmcnt(8)
	s_waitcnt lgkmcnt(0)
	v_pk_fma_f32 v[152:153], v[132:133], v[148:149], v[152:153]
	v_pk_fma_f32 v[154:155], v[134:135], v[150:151], v[154:155]
	v_pk_fma_f32 v[156:157], v[128:129], v[144:145], v[156:157]
	v_pk_fma_f32 v[158:159], v[130:131], v[146:147], v[158:159]
	v_pk_fma_f32 v[160:161], v[124:125], v[140:141], v[160:161]
	v_pk_fma_f32 v[162:163], v[126:127], v[142:143], v[162:163]
	v_pk_fma_f32 v[164:165], v[120:121], v[136:137], v[164:165]
	v_pk_fma_f32 v[166:167], v[122:123], v[138:139], v[166:167]
	global_store_dwordx4 v[218:219], v[152:155], off
	global_store_dwordx4 v[218:219], v[156:159], off offset:64
	global_store_dwordx4 v[218:219], v[160:163], off offset:512
	global_store_dwordx4 v[218:219], v[164:167], off offset:576
	s_mov_b32 s30, 0x10000
	s_mov_b32 s31, 0
	v_lshl_add_u64 v[218:219], v[218:219], 0, s[30:31]
	global_load_dwordx4 v[152:155], v[200:201], off
	global_load_dwordx4 v[156:159], v[200:201], off offset:64
	global_load_dwordx4 v[160:163], v[200:201], off offset:512
	global_load_dwordx4 v[164:167], v[200:201], off offset:576
	s_mov_b32 s30, 0x50000
	s_mov_b32 s31, 0
	v_lshl_add_u64 v[200:201], v[200:201], 0, s[30:31]
	global_load_dwordx4 v[132:135], v[200:201], off
	global_load_dwordx4 v[128:131], v[200:201], off offset:64
	global_load_dwordx4 v[124:127], v[200:201], off offset:512
	global_load_dwordx4 v[120:123], v[200:201], off offset:576
	s_mov_b32 s30, 0x10000
	s_mov_b32 s31, 0
	v_lshl_add_u64 v[200:201], v[200:201], 0, s[30:31]
	ds_bpermute_b32 v116, v198, v116
	ds_bpermute_b32 v117, v198, v117
	ds_bpermute_b32 v118, v198, v118
	ds_bpermute_b32 v119, v198, v119
	ds_bpermute_b32 v112, v198, v112
	ds_bpermute_b32 v113, v198, v113
	ds_bpermute_b32 v114, v198, v114
	ds_bpermute_b32 v115, v198, v115
	ds_bpermute_b32 v108, v198, v108
	ds_bpermute_b32 v109, v198, v109
	ds_bpermute_b32 v110, v198, v110
	ds_bpermute_b32 v111, v198, v111
	ds_bpermute_b32 v104, v198, v104
	ds_bpermute_b32 v105, v198, v105
	ds_bpermute_b32 v106, v198, v106
	ds_bpermute_b32 v107, v198, v107
	s_waitcnt vmcnt(16)
; __device__ __forceinline__ unsigned pk2(float lo, float hi) { const f32v2_t f = {lo, hi}; const bf16v2_t b = __builtin_convertvector(f, bf16v2_t); return __builtin_bit_cast(unsigned, b); }
;     __device__ __forceinline__ void operator()(const f32x4 (&acc)[2][2][4][2], const int upm, const int upn, const int usplit, int wr, int wc, int fr, int fq) const {
;     ...
;         const bool lat = upm * BM < NLAT; const int b = lat ? ((upm * BM) >> 11) : 16;
;         const float* gp = gate + (size_t)b * 6144 + col0;
;         f32x4 gv[2][2];
; #pragma unroll
;         for (int bj = 0; bj < 2; ++bj)
; #pragma unroll
;             for (int n = 0; n < 2; ++n) gv[bj][n] = *(const f32x4*)(gp + bj * HALF + n * 16);
;         const float* sb = lat ? src_lat : src_ctx - (size_t)NLAT * DM; float* db = lat ? dst_lat : dst_ctx - (size_t)NLAT * DM;
; #pragma unroll
;         for (int ai = 0; ai < 2; ++ai)
; #pragma unroll
;             for (int mh = 0; mh < 2; ++mh) {
;                 f32x4 xv[2][2][2];
; #pragma unroll
;                 for (int m = 0; m < 2; ++m)
; #pragma unroll
;                     for (int bj = 0; bj < 2; ++bj)
; #pragma unroll
;                         for (int n = 0; n < 2; ++n) xv[m][bj][n] = *(const f32x4*)(sb + (size_t)(row0 + ai * HALF + (mh * 2 + m) * 16) * DM + col0 + bj * HALF + n * 16);
;                 __builtin_amdgcn_sched_barrier(0);
; #pragma unroll
;                 for (int m = 0; m < 2; ++m)
; #pragma unroll
;                     for (int bj = 0; bj < 2; ++bj)
; #pragma unroll
;                         for (int n = 0; n < 2; ++n) {
;                             const size_t o = (size_t)(row0 + ai * HALF + (mh * 2 + m) * 16) * DM + col0 + bj * HALF + n * 16;
;                             const f32x4 r = xv[m][bj][n] + gv[bj][n] * acc[ai][bj][mh * 2 + m][n];
;                             *(f32x4*)(db + o) = r;
;                             if (xb && lat) { u32x2 pk; pk.x = pk2(r[0], r[1]); pk.y = pk2(r[2], r[3]); *(u32x2*)(xb + o) = pk; }
;                         }
	s_waitcnt lgkmcnt(0)
	v_pk_fma_f32 v[168:169], v[116:117], v[148:149], v[168:169]
	v_pk_fma_f32 v[170:171], v[118:119], v[150:151], v[170:171]
	v_pk_fma_f32 v[172:173], v[112:113], v[144:145], v[172:173]
	v_pk_fma_f32 v[174:175], v[114:115], v[146:147], v[174:175]
	v_pk_fma_f32 v[176:177], v[108:109], v[140:141], v[176:177]
	v_pk_fma_f32 v[178:179], v[110:111], v[142:143], v[178:179]
	v_pk_fma_f32 v[180:181], v[104:105], v[136:137], v[180:181]
	v_pk_fma_f32 v[182:183], v[106:107], v[138:139], v[182:183]
	global_store_dwordx4 v[218:219], v[168:171], off
	global_store_dwordx4 v[218:219], v[172:175], off offset:64
	global_store_dwordx4 v[218:219], v[176:179], off offset:512
	global_store_dwordx4 v[218:219], v[180:183], off offset:576
	s_mov_b32 s30, 0x10000
	s_mov_b32 s31, 0
	v_lshl_add_u64 v[218:219], v[218:219], 0, s[30:31]
	global_load_dwordx4 v[168:171], v[200:201], off
	global_load_dwordx4 v[172:175], v[200:201], off offset:64
	global_load_dwordx4 v[176:179], v[200:201], off offset:512
	global_load_dwordx4 v[180:183], v[200:201], off offset:576
	s_mov_b32 s30, 0x10000
	s_mov_b32 s31, 0
	v_lshl_add_u64 v[200:201], v[200:201], 0, s[30:31]
	global_load_dwordx4 v[116:119], v[200:201], off
	global_load_dwordx4 v[112:115], v[200:201], off offset:64
	global_load_dwordx4 v[108:111], v[200:201], off offset:512
	global_load_dwordx4 v[104:107], v[200:201], off offset:576
	s_mov_b32 s30, 0x10000
	s_mov_b32 s31, 0
	v_lshl_add_u64 v[200:201], v[200:201], 0, s[30:31]
	ds_bpermute_b32 v100, v198, v100
	ds_bpermute_b32 v101, v198, v101
	ds_bpermute_b32 v102, v198, v102
	ds_bpermute_b32 v103, v198, v103
	ds_bpermute_b32 v96, v198, v96
	ds_bpermute_b32 v97, v198, v97
	ds_bpermute_b32 v98, v198, v98
	ds_bpermute_b32 v99, v198, v99
	ds_bpermute_b32 v92, v198, v92
	ds_bpermute_b32 v93, v198, v93
	ds_bpermute_b32 v94, v198, v94
	ds_bpermute_b32 v95, v198, v95
	ds_bpermute_b32 v88, v198, v88
	ds_bpermute_b32 v89, v198, v89
	ds_bpermute_b32 v90, v198, v90
	ds_bpermute_b32 v91, v198, v91
	s_waitcnt vmcnt(24)
	s_waitcnt lgkmcnt(0)
	v_pk_fma_f32 v[190:191], v[100:101], v[148:149], v[190:191]
	v_pk_fma_f32 v[192:193], v[102:103], v[150:151], v[192:193]
	v_pk_fma_f32 v[194:195], v[96:97], v[144:145], v[194:195]
	v_pk_fma_f32 v[196:197], v[98:99], v[146:147], v[196:197]
	v_pk_fma_f32 v[234:235], v[92:93], v[140:141], v[234:235]
	v_pk_fma_f32 v[236:237], v[94:95], v[142:143], v[236:237]
	v_pk_fma_f32 v[238:239], v[88:89], v[136:137], v[238:239]
	v_pk_fma_f32 v[240:241], v[90:91], v[138:139], v[240:241]
	global_store_dwordx4 v[218:219], v[190:193], off
	global_store_dwordx4 v[218:219], v[194:197], off offset:64
	global_store_dwordx4 v[218:219], v[234:237], off offset:512
	global_store_dwordx4 v[218:219], v[238:241], off offset:576
	s_mov_b32 s30, 0x10000
	s_mov_b32 s31, 0
	v_lshl_add_u64 v[218:219], v[218:219], 0, s[30:31]
	global_load_dwordx4 v[190:193], v[200:201], off
	global_load_dwordx4 v[194:197], v[200:201], off offset:64
	global_load_dwordx4 v[234:237], v[200:201], off offset:512
	global_load_dwordx4 v[238:241], v[200:201], off offset:576
	ds_bpermute_b32 v84, v198, v84
	ds_bpermute_b32 v85, v198, v85
	ds_bpermute_b32 v86, v198, v86
	ds_bpermute_b32 v87, v198, v87
	ds_bpermute_b32 v80, v198, v80
	ds_bpermute_b32 v81, v198, v81
	ds_bpermute_b32 v82, v198, v82
	ds_bpermute_b32 v83, v198, v83
	ds_bpermute_b32 v76, v198, v76
	ds_bpermute_b32 v77, v198, v77
	ds_bpermute_b32 v78, v198, v78
	ds_bpermute_b32 v79, v198, v79
	ds_bpermute_b32 v72, v198, v72
	ds_bpermute_b32 v73, v198, v73
	ds_bpermute_b32 v74, v198, v74
	ds_bpermute_b32 v75, v198, v75
	s_waitcnt vmcnt(24)
	s_waitcnt lgkmcnt(0)
	v_pk_fma_f32 v[152:153], v[84:85], v[148:149], v[152:153]
	v_pk_fma_f32 v[154:155], v[86:87], v[150:151], v[154:155]
	v_pk_fma_f32 v[156:157], v[80:81], v[144:145], v[156:157]
	v_pk_fma_f32 v[158:159], v[82:83], v[146:147], v[158:159]
	v_pk_fma_f32 v[160:161], v[76:77], v[140:141], v[160:161]
	v_pk_fma_f32 v[162:163], v[78:79], v[142:143], v[162:163]
	v_pk_fma_f32 v[164:165], v[72:73], v[136:137], v[164:165]
	v_pk_fma_f32 v[166:167], v[74:75], v[138:139], v[166:167]
	global_store_dwordx4 v[218:219], v[152:155], off
	global_store_dwordx4 v[218:219], v[156:159], off offset:64
	global_store_dwordx4 v[218:219], v[160:163], off offset:512
	global_store_dwordx4 v[218:219], v[164:167], off offset:576
	s_mov_b32 s30, 0x50000
	s_mov_b32 s31, 0
	v_lshl_add_u64 v[218:219], v[218:219], 0, s[30:31]
	ds_bpermute_b32 v68, v198, v68
	ds_bpermute_b32 v69, v198, v69
	ds_bpermute_b32 v70, v198, v70
	ds_bpermute_b32 v71, v198, v71
	ds_bpermute_b32 v64, v198, v64
	ds_bpermute_b32 v65, v198, v65
	ds_bpermute_b32 v66, v198, v66
	ds_bpermute_b32 v67, v198, v67
	ds_bpermute_b32 v60, v198, v60
	ds_bpermute_b32 v61, v198, v61
	ds_bpermute_b32 v62, v198, v62
	ds_bpermute_b32 v63, v198, v63
	ds_bpermute_b32 v56, v198, v56
	ds_bpermute_b32 v57, v198, v57
	ds_bpermute_b32 v58, v198, v58
	ds_bpermute_b32 v59, v198, v59
	s_waitcnt vmcnt(24)
; __device__ __forceinline__ unsigned pk2(float lo, float hi) { const f32v2_t f = {lo, hi}; const bf16v2_t b = __builtin_convertvector(f, bf16v2_t); return __builtin_bit_cast(unsigned, b); }
;     __device__ __forceinline__ void operator()(const f32x4 (&acc)[2][2][4][2], const int upm, const int upn, const int usplit, int wr, int wc, int fr, int fq) const {
;     ...
;         const bool lat = upm * BM < NLAT; const int b = lat ? ((upm * BM) >> 11) : 16;
;         const float* gp = gate + (size_t)b * 6144 + col0;
;         f32x4 gv[2][2];
; #pragma unroll
;         for (int bj = 0; bj < 2; ++bj)
; #pragma unroll
;             for (int n = 0; n < 2; ++n) gv[bj][n] = *(const f32x4*)(gp + bj * HALF + n * 16);
;         const float* sb = lat ? src_lat : src_ctx - (size_t)NLAT * DM; float* db = lat ? dst_lat : dst_ctx - (size_t)NLAT * DM;
; #pragma unroll
;         for (int ai = 0; ai < 2; ++ai)
; #pragma unroll
;             for (int mh = 0; mh < 2; ++mh) {
;                 f32x4 xv[2][2][2];
; #pragma unroll
;                 for (int m = 0; m < 2; ++m)
; #pragma unroll
;                     for (int bj = 0; bj < 2; ++bj)
; #pragma unroll
;                         for (int n = 0; n < 2; ++n) xv[m][bj][n] = *(const f32x4*)(sb + (size_t)(row0 + ai * HALF + (mh * 2 + m) * 16) * DM + col0 + bj * HALF + n * 16);
;                 __builtin_amdgcn_sched_barrier(0);
; #pragma unroll
;                 for (int m = 0; m < 2; ++m)
; #pragma unroll
;                     for (int bj = 0; bj < 2; ++bj)
; #pragma unroll
;                         for (int n = 0; n < 2; ++n) {
;                             const size_t o = (size_t)(row0 + ai * HALF + (mh * 2 + m) * 16) * DM + col0 + bj * HALF + n * 16;
;                             const f32x4 r = xv[m][bj][n] + gv[bj][n] * acc[ai][bj][mh * 2 + m][n];
;                             *(f32x4*)(db + o) = r;
;                             if (xb && lat) { u32x2 pk; pk.x = pk2(r[0], r[1]); pk.y = pk2(r[2], r[3]); *(u32x2*)(xb + o) = pk; }
;                         }
	s_waitcnt lgkmcnt(0)
	v_pk_fma_f32 v[132:133], v[68:69], v[148:149], v[132:133]
	v_pk_fma_f32 v[134:135], v[70:71], v[150:151], v[134:135]
	v_pk_fma_f32 v[128:129], v[64:65], v[144:145], v[128:129]
	v_pk_fma_f32 v[130:131], v[66:67], v[146:147], v[130:131]
	v_pk_fma_f32 v[124:125], v[60:61], v[140:141], v[124:125]
	v_pk_fma_f32 v[126:127], v[62:63], v[142:143], v[126:127]
	v_pk_fma_f32 v[120:121], v[56:57], v[136:137], v[120:121]
	v_pk_fma_f32 v[122:123], v[58:59], v[138:139], v[122:123]
	global_store_dwordx4 v[218:219], v[132:135], off
	global_store_dwordx4 v[218:219], v[128:131], off offset:64
	global_store_dwordx4 v[218:219], v[124:127], off offset:512
	global_store_dwordx4 v[218:219], v[120:123], off offset:576
	s_mov_b32 s30, 0x10000
	s_mov_b32 s31, 0
	v_lshl_add_u64 v[218:219], v[218:219], 0, s[30:31]
	ds_bpermute_b32 v52, v198, v52
	ds_bpermute_b32 v53, v198, v53
	ds_bpermute_b32 v54, v198, v54
	ds_bpermute_b32 v55, v198, v55
	ds_bpermute_b32 v48, v198, v48
	ds_bpermute_b32 v49, v198, v49
	ds_bpermute_b32 v50, v198, v50
	ds_bpermute_b32 v51, v198, v51
	ds_bpermute_b32 v44, v198, v44
	ds_bpermute_b32 v45, v198, v45
	ds_bpermute_b32 v46, v198, v46
	ds_bpermute_b32 v47, v198, v47
	ds_bpermute_b32 v40, v198, v40
	ds_bpermute_b32 v41, v198, v41
	ds_bpermute_b32 v42, v198, v42
	ds_bpermute_b32 v43, v198, v43
	s_waitcnt vmcnt(20)
	s_waitcnt lgkmcnt(0)
	v_pk_fma_f32 v[168:169], v[52:53], v[148:149], v[168:169]
	v_pk_fma_f32 v[170:171], v[54:55], v[150:151], v[170:171]
	v_pk_fma_f32 v[172:173], v[48:49], v[144:145], v[172:173]
	v_pk_fma_f32 v[174:175], v[50:51], v[146:147], v[174:175]
	v_pk_fma_f32 v[176:177], v[44:45], v[140:141], v[176:177]
	v_pk_fma_f32 v[178:179], v[46:47], v[142:143], v[178:179]
	v_pk_fma_f32 v[180:181], v[40:41], v[136:137], v[180:181]
	v_pk_fma_f32 v[182:183], v[42:43], v[138:139], v[182:183]
	global_store_dwordx4 v[218:219], v[168:171], off
	global_store_dwordx4 v[218:219], v[172:175], off offset:64
	global_store_dwordx4 v[218:219], v[176:179], off offset:512
	global_store_dwordx4 v[218:219], v[180:183], off offset:576
	s_mov_b32 s30, 0x10000
	s_mov_b32 s31, 0
	v_lshl_add_u64 v[218:219], v[218:219], 0, s[30:31]
	ds_bpermute_b32 v36, v198, v36
	ds_bpermute_b32 v37, v198, v37
	ds_bpermute_b32 v38, v198, v38
	ds_bpermute_b32 v39, v198, v39
	ds_bpermute_b32 v32, v198, v32
	ds_bpermute_b32 v33, v198, v33
	ds_bpermute_b32 v34, v198, v34
	ds_bpermute_b32 v35, v198, v35
	ds_bpermute_b32 v28, v198, v28
	ds_bpermute_b32 v29, v198, v29
	ds_bpermute_b32 v30, v198, v30
	ds_bpermute_b32 v31, v198, v31
	ds_bpermute_b32 v24, v198, v24
	ds_bpermute_b32 v25, v198, v25
	ds_bpermute_b32 v26, v198, v26
	ds_bpermute_b32 v27, v198, v27
	s_waitcnt vmcnt(20)
	s_waitcnt lgkmcnt(0)
	v_pk_fma_f32 v[116:117], v[36:37], v[148:149], v[116:117]
	v_pk_fma_f32 v[118:119], v[38:39], v[150:151], v[118:119]
	v_pk_fma_f32 v[112:113], v[32:33], v[144:145], v[112:113]
	v_pk_fma_f32 v[114:115], v[34:35], v[146:147], v[114:115]
	v_pk_fma_f32 v[108:109], v[28:29], v[140:141], v[108:109]
	v_pk_fma_f32 v[110:111], v[30:31], v[142:143], v[110:111]
	v_pk_fma_f32 v[104:105], v[24:25], v[136:137], v[104:105]
	v_pk_fma_f32 v[106:107], v[26:27], v[138:139], v[106:107]
	global_store_dwordx4 v[218:219], v[116:119], off
	global_store_dwordx4 v[218:219], v[112:115], off offset:64
	global_store_dwordx4 v[218:219], v[108:111], off offset:512
	global_store_dwordx4 v[218:219], v[104:107], off offset:576
	s_mov_b32 s30, 0x10000
	s_mov_b32 s31, 0
	v_lshl_add_u64 v[218:219], v[218:219], 0, s[30:31]
	ds_bpermute_b32 v20, v198, v20
	ds_bpermute_b32 v21, v198, v21
	ds_bpermute_b32 v22, v198, v22
	ds_bpermute_b32 v23, v198, v23
	ds_bpermute_b32 v16, v198, v16
	ds_bpermute_b32 v17, v198, v17
	ds_bpermute_b32 v18, v198, v18
	ds_bpermute_b32 v19, v198, v19
	ds_bpermute_b32 v12, v198, v12
	ds_bpermute_b32 v13, v198, v13
	ds_bpermute_b32 v14, v198, v14
	ds_bpermute_b32 v15, v198, v15
	ds_bpermute_b32 v8, v198, v8
	ds_bpermute_b32 v9, v198, v9
	ds_bpermute_b32 v10, v198, v10
	ds_bpermute_b32 v11, v198, v11
	s_waitcnt vmcnt(16)
	s_waitcnt lgkmcnt(0)
	v_pk_fma_f32 v[190:191], v[20:21], v[148:149], v[190:191]
	v_pk_fma_f32 v[192:193], v[22:23], v[150:151], v[192:193]
	v_pk_fma_f32 v[194:195], v[16:17], v[144:145], v[194:195]
	v_pk_fma_f32 v[196:197], v[18:19], v[146:147], v[196:197]
	v_pk_fma_f32 v[234:235], v[12:13], v[140:141], v[234:235]
	v_pk_fma_f32 v[236:237], v[14:15], v[142:143], v[236:237]
	v_pk_fma_f32 v[238:239], v[8:9], v[136:137], v[238:239]
	v_pk_fma_f32 v[240:241], v[10:11], v[138:139], v[240:241]
	global_store_dwordx4 v[218:219], v[190:193], off
	global_store_dwordx4 v[218:219], v[194:197], off offset:64
	global_store_dwordx4 v[218:219], v[234:237], off offset:512
	global_store_dwordx4 v[218:219], v[238:241], off offset:576
	s_branch .LBB0_1481

; __device__ __forceinline__ unsigned pk2(float lo, float hi) { const f32v2_t f = {lo, hi}; const bf16v2_t b = __builtin_convertvector(f, bf16v2_t); return __builtin_bit_cast(unsigned, b); }
;     __device__ __forceinline__ void operator()(const f32x4 (&acc)[2][2][4][2], const int upm, const int upn, const int usplit, int wr, int wc, int fr, int fq) const {
;     ...
;         const bool lat = upm * BM < NLAT; const int b = lat ? ((upm * BM) >> 11) : 16;
;         const float* gp = gate + (size_t)b * 6144 + col0;
;         f32x4 gv[2][2];
; #pragma unroll
;         for (int bj = 0; bj < 2; ++bj)
; #pragma unroll
;             for (int n = 0; n < 2; ++n) gv[bj][n] = *(const f32x4*)(gp + bj * HALF + n * 16);
;         const float* sb = lat ? src_lat : src_ctx - (size_t)NLAT * DM; float* db = lat ? dst_lat : dst_ctx - (size_t)NLAT * DM;
; #pragma unroll
;         for (int ai = 0; ai < 2; ++ai)
; #pragma unroll
;             for (int mh = 0; mh < 2; ++mh) {
;                 f32x4 xv[2][2][2];
; #pragma unroll
;                 for (int m = 0; m < 2; ++m)
; #pragma unroll
;                     for (int bj = 0; bj < 2; ++bj)
; #pragma unroll
;                         for (int n = 0; n < 2; ++n) xv[m][bj][n] = *(const f32x4*)(sb + (size_t)(row0 + ai * HALF + (mh * 2 + m) * 16) * DM + col0 + bj * HALF + n * 16);
;                 __builtin_amdgcn_sched_barrier(0);
; #pragma unroll
;                 for (int m = 0; m < 2; ++m)
; #pragma unroll
;                     for (int bj = 0; bj < 2; ++bj)
; #pragma unroll
;                         for (int n = 0; n < 2; ++n) {
;                             const size_t o = (size_t)(row0 + ai * HALF + (mh * 2 + m) * 16) * DM + col0 + bj * HALF + n * 16;
;                             const f32x4 r = xv[m][bj][n] + gv[bj][n] * acc[ai][bj][mh * 2 + m][n];
;                             *(f32x4*)(db + o) = r;
;                             if (xb && lat) { u32x2 pk; pk.x = pk2(r[0], r[1]); pk.y = pk2(r[2], r[3]); *(u32x2*)(xb + o) = pk; }
;                         }
.LBB0_1866:
	s_lshl_b64 s[0:1], s[60:61], 2
	s_add_u32 s0, s21, s0
	s_addc_u32 s1, s69, s1
	v_mbcnt_lo_u32_b32 v152, -1, 0
	v_mbcnt_hi_u32_b32 v152, -1, v152
	v_and_b32_e32 v153, 15, v152
	v_lshrrev_b32_e32 v154, 2, v152
	v_lshrrev_b32_e32 v155, 4, v152
	v_and_b32_e32 v156, 3, v152
	v_sub_u32_e32 v192, v192, v153
	v_add_u32_e32 v192, v192, v154
	v_ashrrev_i32_e32 v193, 31, v192
	v_sub_u32_e32 v157, v156, v155
	v_lshl_add_u32 v190, v157, 2, v190
	v_ashrrev_i32_e32 v191, 31, v190
	v_lshl_add_u32 v158, v156, 4, v154
	v_lshlrev_b64 v[198:199], 2, v[190:191]
	v_lshl_add_u64 v[242:243], s[0:1], 0, v[198:199]
	v_lshl_add_u64 v[200:201], s[58:59], 0, v[198:199]
	v_lshl_add_u64 v[218:219], s[58:59], 0, v[198:199]
	v_lshlrev_b64 v[198:199], 12, v[192:193]
	v_lshl_add_u64 v[200:201], v[200:201], 0, v[198:199]
	v_lshl_add_u64 v[218:219], v[218:219], 0, v[198:199]
	global_load_dwordx4 v[148:151], v[242:243], off
	global_load_dwordx4 v[144:147], v[242:243], off offset:64
	global_load_dwordx4 v[140:143], v[242:243], off offset:512
	global_load_dwordx4 v[136:139], v[242:243], off offset:576
	v_lshlrev_b64 v[198:199], 1, v[190:191]
	v_lshl_add_u64 v[242:243], s[40:41], 0, v[198:199]
	v_lshlrev_b64 v[198:199], 11, v[192:193]
	v_lshl_add_u64 v[242:243], v[242:243], 0, v[198:199]
	v_lshlrev_b32_e32 v198, 2, v158
	global_load_dwordx4 v[152:155], v[200:201], off
	global_load_dwordx4 v[156:159], v[200:201], off offset:64
	global_load_dwordx4 v[160:163], v[200:201], off offset:512
	global_load_dwordx4 v[164:167], v[200:201], off offset:576
	s_mov_b32 s0, 0x10000
	s_mov_b32 s1, 0
	v_lshl_add_u64 v[200:201], v[200:201], 0, s[0:1]
	global_load_dwordx4 v[168:171], v[200:201], off
	global_load_dwordx4 v[172:175], v[200:201], off offset:64
	global_load_dwordx4 v[176:179], v[200:201], off offset:512
	global_load_dwordx4 v[180:183], v[200:201], off offset:576
	s_mov_b32 s0, 0x10000
	s_mov_b32 s1, 0
	v_lshl_add_u64 v[200:201], v[200:201], 0, s[0:1]
	global_load_dwordx4 v[190:193], v[200:201], off
	global_load_dwordx4 v[194:197], v[200:201], off offset:64
	global_load_dwordx4 v[234:237], v[200:201], off offset:512
	global_load_dwordx4 v[238:241], v[200:201], off offset:576
	s_mov_b32 s0, 0x10000
	s_mov_b32 s1, 0
	v_lshl_add_u64 v[200:201], v[200:201], 0, s[0:1]
	s_and_b64 s[0:1], s[46:47], s[56:57]
	s_xor_b64 s[56:57], s[0:1], -1
	s_and_b64 vcc, exec, s[56:57]
	s_cbranch_vccnz .Lmy_epi_p7_nobf
	ds_bpermute_b32 v132, v198, v132
	ds_bpermute_b32 v133, v198, v133
	ds_bpermute_b32 v134, v198, v134
	ds_bpermute_b32 v135, v198, v135
	ds_bpermute_b32 v128, v198, v128
	ds_bpermute_b32 v129, v198, v129
	ds_bpermute_b32 v130, v198, v130
	ds_bpermute_b32 v131, v198, v131
	ds_bpermute_b32 v124, v198, v124
	ds_bpermute_b32 v125, v198, v125
	ds_bpermute_b32 v126, v198, v126
	ds_bpermute_b32 v127, v198, v127
	ds_bpermute_b32 v120, v198, v120
	ds_bpermute_b32 v121, v198, v121
	ds_bpermute_b32 v122, v198, v122
	ds_bpermute_b32 v123, v198, v123
	s_waitcnt vmcnt(8)
	s_waitcnt lgkmcnt(0)
	v_pk_fma_f32 v[152:153], v[132:133], v[148:149], v[152:153]
	v_pk_fma_f32 v[154:155], v[134:135], v[150:151], v[154:155]
	v_pk_fma_f32 v[156:157], v[128:129], v[144:145], v[156:157]
	v_pk_fma_f32 v[158:159], v[130:131], v[146:147], v[158:159]
	v_pk_fma_f32 v[160:161], v[124:125], v[140:141], v[160:161]
	v_pk_fma_f32 v[162:163], v[126:127], v[142:143], v[162:163]
	v_pk_fma_f32 v[164:165], v[120:121], v[136:137], v[164:165]
	v_pk_fma_f32 v[166:167], v[122:123], v[138:139], v[166:167]
	global_store_dwordx4 v[218:219], v[152:155], off
	global_store_dwordx4 v[218:219], v[156:159], off offset:64
	global_store_dwordx4 v[218:219], v[160:163], off offset:512
	global_store_dwordx4 v[218:219], v[164:167], off offset:576
	v_cvt_pk_bf16_f32 v132, v152, v153
	v_cvt_pk_bf16_f32 v133, v154, v155
	v_cvt_pk_bf16_f32 v128, v156, v157
	v_cvt_pk_bf16_f32 v129, v158, v159
	v_cvt_pk_bf16_f32 v124, v160, v161
	v_cvt_pk_bf16_f32 v125, v162, v163
	v_cvt_pk_bf16_f32 v120, v164, v165
	v_cvt_pk_bf16_f32 v121, v166, v167
	global_store_dwordx2 v[242:243], v[132:133], off
	global_store_dwordx2 v[242:243], v[128:129], off offset:32
	global_store_dwordx2 v[242:243], v[124:125], off offset:256
	global_store_dwordx2 v[242:243], v[120:121], off offset:288
	s_mov_b32 s0, 0x10000
	s_mov_b32 s1, 0
	v_lshl_add_u64 v[218:219], v[218:219], 0, s[0:1]
	s_mov_b32 s0, 0x8000
	s_mov_b32 s1, 0
	v_lshl_add_u64 v[242:243], v[242:243], 0, s[0:1]
	global_load_dwordx4 v[152:155], v[200:201], off
	global_load_dwordx4 v[156:159], v[200:201], off offset:64
	global_load_dwordx4 v[160:163], v[200:201], off offset:512
	global_load_dwordx4 v[164:167], v[200:201], off offset:576
	s_mov_b32 s0, 0x50000
	s_mov_b32 s1, 0
	v_lshl_add_u64 v[200:201], v[200:201], 0, s[0:1]
	global_load_dwordx4 v[132:135], v[200:201], off
	global_load_dwordx4 v[128:131], v[200:201], off offset:64
	global_load_dwordx4 v[124:127], v[200:201], off offset:512
	global_load_dwordx4 v[120:123], v[200:201], off offset:576
	s_mov_b32 s0, 0x10000
	s_mov_b32 s1, 0
	v_lshl_add_u64 v[200:201], v[200:201], 0, s[0:1]
	ds_bpermute_b32 v116, v198, v116
	ds_bpermute_b32 v117, v198, v117
	ds_bpermute_b32 v118, v198, v118
	ds_bpermute_b32 v119, v198, v119
	ds_bpermute_b32 v112, v198, v112
	ds_bpermute_b32 v113, v198, v113
	ds_bpermute_b32 v114, v198, v114
	ds_bpermute_b32 v115, v198, v115
	ds_bpermute_b32 v108, v198, v108
	ds_bpermute_b32 v109, v198, v109
	ds_bpermute_b32 v110, v198, v110
	ds_bpermute_b32 v111, v198, v111
	ds_bpermute_b32 v104, v198, v104
	ds_bpermute_b32 v105, v198, v105
	ds_bpermute_b32 v106, v198, v106
	ds_bpermute_b32 v107, v198, v107
	s_waitcnt vmcnt(20)
	s_waitcnt lgkmcnt(0)
; __device__ __forceinline__ unsigned pk2(float lo, float hi) { const f32v2_t f = {lo, hi}; const bf16v2_t b = __builtin_convertvector(f, bf16v2_t); return __builtin_bit_cast(unsigned, b); }
;     __device__ __forceinline__ void operator()(const f32x4 (&acc)[2][2][4][2], const int upm, const int upn, const int usplit, int wr, int wc, int fr, int fq) const {
;     ...
;         const bool lat = upm * BM < NLAT; const int b = lat ? ((upm * BM) >> 11) : 16;
;         const float* gp = gate + (size_t)b * 6144 + col0;
;         f32x4 gv[2][2];
; #pragma unroll
;         for (int bj = 0; bj < 2; ++bj)
; #pragma unroll
;             for (int n = 0; n < 2; ++n) gv[bj][n] = *(const f32x4*)(gp + bj * HALF + n * 16);
;         const float* sb = lat ? src_lat : src_ctx - (size_t)NLAT * DM; float* db = lat ? dst_lat : dst_ctx - (size_t)NLAT * DM;
; #pragma unroll
;         for (int ai = 0; ai < 2; ++ai)
; #pragma unroll
;             for (int mh = 0; mh < 2; ++mh) {
;                 f32x4 xv[2][2][2];
; #pragma unroll
;                 for (int m = 0; m < 2; ++m)
; #pragma unroll
;                     for (int bj = 0; bj < 2; ++bj)
; #pragma unroll
;                         for (int n = 0; n < 2; ++n) xv[m][bj][n] = *(const f32x4*)(sb + (size_t)(row0 + ai * HALF + (mh * 2 + m) * 16) * DM + col0 + bj * HALF + n * 16);
;                 __builtin_amdgcn_sched_barrier(0);
; #pragma unroll
;                 for (int m = 0; m < 2; ++m)
; #pragma unroll
;                     for (int bj = 0; bj < 2; ++bj)
; #pragma unroll
;                         for (int n = 0; n < 2; ++n) {
;                             const size_t o = (size_t)(row0 + ai * HALF + (mh * 2 + m) * 16) * DM + col0 + bj * HALF + n * 16;
;                             const f32x4 r = xv[m][bj][n] + gv[bj][n] * acc[ai][bj][mh * 2 + m][n];
;                             *(f32x4*)(db + o) = r;
;                             if (xb && lat) { u32x2 pk; pk.x = pk2(r[0], r[1]); pk.y = pk2(r[2], r[3]); *(u32x2*)(xb + o) = pk; }
;                         }
	v_pk_fma_f32 v[168:169], v[116:117], v[148:149], v[168:169]
	v_pk_fma_f32 v[170:171], v[118:119], v[150:151], v[170:171]
	v_pk_fma_f32 v[172:173], v[112:113], v[144:145], v[172:173]
	v_pk_fma_f32 v[174:175], v[114:115], v[146:147], v[174:175]
	v_pk_fma_f32 v[176:177], v[108:109], v[140:141], v[176:177]
	v_pk_fma_f32 v[178:179], v[110:111], v[142:143], v[178:179]
	v_pk_fma_f32 v[180:181], v[104:105], v[136:137], v[180:181]
	v_pk_fma_f32 v[182:183], v[106:107], v[138:139], v[182:183]
	global_store_dwordx4 v[218:219], v[168:171], off
	global_store_dwordx4 v[218:219], v[172:175], off offset:64
	global_store_dwordx4 v[218:219], v[176:179], off offset:512
	global_store_dwordx4 v[218:219], v[180:183], off offset:576
	v_cvt_pk_bf16_f32 v116, v168, v169
	v_cvt_pk_bf16_f32 v117, v170, v171
	v_cvt_pk_bf16_f32 v112, v172, v173
	v_cvt_pk_bf16_f32 v113, v174, v175
	v_cvt_pk_bf16_f32 v108, v176, v177
	v_cvt_pk_bf16_f32 v109, v178, v179
	v_cvt_pk_bf16_f32 v104, v180, v181
	v_cvt_pk_bf16_f32 v105, v182, v183
	global_store_dwordx2 v[242:243], v[116:117], off
	global_store_dwordx2 v[242:243], v[112:113], off offset:32
	global_store_dwordx2 v[242:243], v[108:109], off offset:256
	global_store_dwordx2 v[242:243], v[104:105], off offset:288
	s_mov_b32 s0, 0x10000
	s_mov_b32 s1, 0
	v_lshl_add_u64 v[218:219], v[218:219], 0, s[0:1]
	s_mov_b32 s0, 0x8000
	s_mov_b32 s1, 0
	v_lshl_add_u64 v[242:243], v[242:243], 0, s[0:1]
	global_load_dwordx4 v[168:171], v[200:201], off
	global_load_dwordx4 v[172:175], v[200:201], off offset:64
	global_load_dwordx4 v[176:179], v[200:201], off offset:512
	global_load_dwordx4 v[180:183], v[200:201], off offset:576
	s_mov_b32 s0, 0x10000
	s_mov_b32 s1, 0
	v_lshl_add_u64 v[200:201], v[200:201], 0, s[0:1]
	global_load_dwordx4 v[116:119], v[200:201], off
	global_load_dwordx4 v[112:115], v[200:201], off offset:64
	global_load_dwordx4 v[108:111], v[200:201], off offset:512
	global_load_dwordx4 v[104:107], v[200:201], off offset:576
	s_mov_b32 s0, 0x10000
	s_mov_b32 s1, 0
	v_lshl_add_u64 v[200:201], v[200:201], 0, s[0:1]
	ds_bpermute_b32 v100, v198, v100
	ds_bpermute_b32 v101, v198, v101
	ds_bpermute_b32 v102, v198, v102
	ds_bpermute_b32 v103, v198, v103
	ds_bpermute_b32 v96, v198, v96
	ds_bpermute_b32 v97, v198, v97
	ds_bpermute_b32 v98, v198, v98
	ds_bpermute_b32 v99, v198, v99
	ds_bpermute_b32 v92, v198, v92
	ds_bpermute_b32 v93, v198, v93
	ds_bpermute_b32 v94, v198, v94
	ds_bpermute_b32 v95, v198, v95
	ds_bpermute_b32 v88, v198, v88
	ds_bpermute_b32 v89, v198, v89
	ds_bpermute_b32 v90, v198, v90
	ds_bpermute_b32 v91, v198, v91
	s_waitcnt vmcnt(32)
	s_waitcnt lgkmcnt(0)
	v_pk_fma_f32 v[190:191], v[100:101], v[148:149], v[190:191]
	v_pk_fma_f32 v[192:193], v[102:103], v[150:151], v[192:193]
	v_pk_fma_f32 v[194:195], v[96:97], v[144:145], v[194:195]
	v_pk_fma_f32 v[196:197], v[98:99], v[146:147], v[196:197]
	v_pk_fma_f32 v[234:235], v[92:93], v[140:141], v[234:235]
	v_pk_fma_f32 v[236:237], v[94:95], v[142:143], v[236:237]
	v_pk_fma_f32 v[238:239], v[88:89], v[136:137], v[238:239]
	v_pk_fma_f32 v[240:241], v[90:91], v[138:139], v[240:241]
	global_store_dwordx4 v[218:219], v[190:193], off
	global_store_dwordx4 v[218:219], v[194:197], off offset:64
	global_store_dwordx4 v[218:219], v[234:237], off offset:512
	global_store_dwordx4 v[218:219], v[238:241], off offset:576
	v_cvt_pk_bf16_f32 v100, v190, v191
	v_cvt_pk_bf16_f32 v101, v192, v193
	v_cvt_pk_bf16_f32 v96, v194, v195
	v_cvt_pk_bf16_f32 v97, v196, v197
	v_cvt_pk_bf16_f32 v92, v234, v235
	v_cvt_pk_bf16_f32 v93, v236, v237
	v_cvt_pk_bf16_f32 v88, v238, v239
	v_cvt_pk_bf16_f32 v89, v240, v241
	global_store_dwordx2 v[242:243], v[100:101], off
	global_store_dwordx2 v[242:243], v[96:97], off offset:32
	global_store_dwordx2 v[242:243], v[92:93], off offset:256
	global_store_dwordx2 v[242:243], v[88:89], off offset:288
	s_mov_b32 s0, 0x10000
	s_mov_b32 s1, 0
	v_lshl_add_u64 v[218:219], v[218:219], 0, s[0:1]
	s_mov_b32 s0, 0x8000
	s_mov_b32 s1, 0
	v_lshl_add_u64 v[242:243], v[242:243], 0, s[0:1]
	global_load_dwordx4 v[190:193], v[200:201], off
	global_load_dwordx4 v[194:197], v[200:201], off offset:64
	global_load_dwordx4 v[234:237], v[200:201], off offset:512
	global_load_dwordx4 v[238:241], v[200:201], off offset:576
	ds_bpermute_b32 v84, v198, v84
	ds_bpermute_b32 v85, v198, v85
	ds_bpermute_b32 v86, v198, v86
	ds_bpermute_b32 v87, v198, v87
	ds_bpermute_b32 v80, v198, v80
	ds_bpermute_b32 v81, v198, v81
	ds_bpermute_b32 v82, v198, v82
	ds_bpermute_b32 v83, v198, v83
	ds_bpermute_b32 v76, v198, v76
	ds_bpermute_b32 v77, v198, v77
	ds_bpermute_b32 v78, v198, v78
	ds_bpermute_b32 v79, v198, v79
	ds_bpermute_b32 v72, v198, v72
	ds_bpermute_b32 v73, v198, v73
	ds_bpermute_b32 v74, v198, v74
	ds_bpermute_b32 v75, v198, v75
	s_waitcnt vmcnt(32)
	s_waitcnt lgkmcnt(0)
; __device__ __forceinline__ unsigned pk2(float lo, float hi) { const f32v2_t f = {lo, hi}; const bf16v2_t b = __builtin_convertvector(f, bf16v2_t); return __builtin_bit_cast(unsigned, b); }
;     __device__ __forceinline__ void operator()(const f32x4 (&acc)[2][2][4][2], const int upm, const int upn, const int usplit, int wr, int wc, int fr, int fq) const {
;     ...
;         const bool lat = upm * BM < NLAT; const int b = lat ? ((upm * BM) >> 11) : 16;
;         const float* gp = gate + (size_t)b * 6144 + col0;
;         f32x4 gv[2][2];
; #pragma unroll
;         for (int bj = 0; bj < 2; ++bj)
; #pragma unroll
;             for (int n = 0; n < 2; ++n) gv[bj][n] = *(const f32x4*)(gp + bj * HALF + n * 16);
;         const float* sb = lat ? src_lat : src_ctx - (size_t)NLAT * DM; float* db = lat ? dst_lat : dst_ctx - (size_t)NLAT * DM;
; #pragma unroll
;         for (int ai = 0; ai < 2; ++ai)
; #pragma unroll
;             for (int mh = 0; mh < 2; ++mh) {
;                 f32x4 xv[2][2][2];
; #pragma unroll
;                 for (int m = 0; m < 2; ++m)
; #pragma unroll
;                     for (int bj = 0; bj < 2; ++bj)
; #pragma unroll
;                         for (int n = 0; n < 2; ++n) xv[m][bj][n] = *(const f32x4*)(sb + (size_t)(row0 + ai * HALF + (mh * 2 + m) * 16) * DM + col0 + bj * HALF + n * 16);
;                 __builtin_amdgcn_sched_barrier(0);
; #pragma unroll
;                 for (int m = 0; m < 2; ++m)
; #pragma unroll
;                     for (int bj = 0; bj < 2; ++bj)
; #pragma unroll
;                         for (int n = 0; n < 2; ++n) {
;                             const size_t o = (size_t)(row0 + ai * HALF + (mh * 2 + m) * 16) * DM + col0 + bj * HALF + n * 16;
;                             const f32x4 r = xv[m][bj][n] + gv[bj][n] * acc[ai][bj][mh * 2 + m][n];
;                             *(f32x4*)(db + o) = r;
;                             if (xb && lat) { u32x2 pk; pk.x = pk2(r[0], r[1]); pk.y = pk2(r[2], r[3]); *(u32x2*)(xb + o) = pk; }
;                         }
	v_pk_fma_f32 v[152:153], v[84:85], v[148:149], v[152:153]
	v_pk_fma_f32 v[154:155], v[86:87], v[150:151], v[154:155]
	v_pk_fma_f32 v[156:157], v[80:81], v[144:145], v[156:157]
	v_pk_fma_f32 v[158:159], v[82:83], v[146:147], v[158:159]
	v_pk_fma_f32 v[160:161], v[76:77], v[140:141], v[160:161]
	v_pk_fma_f32 v[162:163], v[78:79], v[142:143], v[162:163]
	v_pk_fma_f32 v[164:165], v[72:73], v[136:137], v[164:165]
	v_pk_fma_f32 v[166:167], v[74:75], v[138:139], v[166:167]
	global_store_dwordx4 v[218:219], v[152:155], off
	global_store_dwordx4 v[218:219], v[156:159], off offset:64
	global_store_dwordx4 v[218:219], v[160:163], off offset:512
	global_store_dwordx4 v[218:219], v[164:167], off offset:576
	v_cvt_pk_bf16_f32 v84, v152, v153
	v_cvt_pk_bf16_f32 v85, v154, v155
	v_cvt_pk_bf16_f32 v80, v156, v157
	v_cvt_pk_bf16_f32 v81, v158, v159
	v_cvt_pk_bf16_f32 v76, v160, v161
	v_cvt_pk_bf16_f32 v77, v162, v163
	v_cvt_pk_bf16_f32 v72, v164, v165
	v_cvt_pk_bf16_f32 v73, v166, v167
	global_store_dwordx2 v[242:243], v[84:85], off
	global_store_dwordx2 v[242:243], v[80:81], off offset:32
	global_store_dwordx2 v[242:243], v[76:77], off offset:256
	global_store_dwordx2 v[242:243], v[72:73], off offset:288
	s_mov_b32 s0, 0x50000
	s_mov_b32 s1, 0
	v_lshl_add_u64 v[218:219], v[218:219], 0, s[0:1]
	s_mov_b32 s0, 0x28000
	s_mov_b32 s1, 0
	v_lshl_add_u64 v[242:243], v[242:243], 0, s[0:1]
	ds_bpermute_b32 v68, v198, v68
	ds_bpermute_b32 v69, v198, v69
	ds_bpermute_b32 v70, v198, v70
	ds_bpermute_b32 v71, v198, v71
	ds_bpermute_b32 v64, v198, v64
	ds_bpermute_b32 v65, v198, v65
	ds_bpermute_b32 v66, v198, v66
	ds_bpermute_b32 v67, v198, v67
	ds_bpermute_b32 v60, v198, v60
	ds_bpermute_b32 v61, v198, v61
	ds_bpermute_b32 v62, v198, v62
	ds_bpermute_b32 v63, v198, v63
	ds_bpermute_b32 v56, v198, v56
	ds_bpermute_b32 v57, v198, v57
	ds_bpermute_b32 v58, v198, v58
	ds_bpermute_b32 v59, v198, v59
	s_waitcnt vmcnt(36)
	s_waitcnt lgkmcnt(0)
	v_pk_fma_f32 v[132:133], v[68:69], v[148:149], v[132:133]
	v_pk_fma_f32 v[134:135], v[70:71], v[150:151], v[134:135]
	v_pk_fma_f32 v[128:129], v[64:65], v[144:145], v[128:129]
	v_pk_fma_f32 v[130:131], v[66:67], v[146:147], v[130:131]
	v_pk_fma_f32 v[124:125], v[60:61], v[140:141], v[124:125]
	v_pk_fma_f32 v[126:127], v[62:63], v[142:143], v[126:127]
	v_pk_fma_f32 v[120:121], v[56:57], v[136:137], v[120:121]
	v_pk_fma_f32 v[122:123], v[58:59], v[138:139], v[122:123]
	global_store_dwordx4 v[218:219], v[132:135], off
	global_store_dwordx4 v[218:219], v[128:131], off offset:64
	global_store_dwordx4 v[218:219], v[124:127], off offset:512
	global_store_dwordx4 v[218:219], v[120:123], off offset:576
	v_cvt_pk_bf16_f32 v68, v132, v133
	v_cvt_pk_bf16_f32 v69, v134, v135
	v_cvt_pk_bf16_f32 v64, v128, v129
	v_cvt_pk_bf16_f32 v65, v130, v131
	v_cvt_pk_bf16_f32 v60, v124, v125
	v_cvt_pk_bf16_f32 v61, v126, v127
	v_cvt_pk_bf16_f32 v56, v120, v121
	v_cvt_pk_bf16_f32 v57, v122, v123
	global_store_dwordx2 v[242:243], v[68:69], off
	global_store_dwordx2 v[242:243], v[64:65], off offset:32
	global_store_dwordx2 v[242:243], v[60:61], off offset:256
	global_store_dwordx2 v[242:243], v[56:57], off offset:288
	s_mov_b32 s0, 0x10000
	s_mov_b32 s1, 0
	v_lshl_add_u64 v[218:219], v[218:219], 0, s[0:1]
	s_mov_b32 s0, 0x8000
	s_mov_b32 s1, 0
	v_lshl_add_u64 v[242:243], v[242:243], 0, s[0:1]
	ds_bpermute_b32 v52, v198, v52
	ds_bpermute_b32 v53, v198, v53
	ds_bpermute_b32 v54, v198, v54
	ds_bpermute_b32 v55, v198, v55
	ds_bpermute_b32 v48, v198, v48
	ds_bpermute_b32 v49, v198, v49
	ds_bpermute_b32 v50, v198, v50
	ds_bpermute_b32 v51, v198, v51
	ds_bpermute_b32 v44, v198, v44
	ds_bpermute_b32 v45, v198, v45
	ds_bpermute_b32 v46, v198, v46
	ds_bpermute_b32 v47, v198, v47
	ds_bpermute_b32 v40, v198, v40
	ds_bpermute_b32 v41, v198, v41
	ds_bpermute_b32 v42, v198, v42
	ds_bpermute_b32 v43, v198, v43
	s_waitcnt vmcnt(32)
	s_waitcnt lgkmcnt(0)
	v_pk_fma_f32 v[168:169], v[52:53], v[148:149], v[168:169]
	v_pk_fma_f32 v[170:171], v[54:55], v[150:151], v[170:171]
	v_pk_fma_f32 v[172:173], v[48:49], v[144:145], v[172:173]
	v_pk_fma_f32 v[174:175], v[50:51], v[146:147], v[174:175]
	v_pk_fma_f32 v[176:177], v[44:45], v[140:141], v[176:177]
	v_pk_fma_f32 v[178:179], v[46:47], v[142:143], v[178:179]
	v_pk_fma_f32 v[180:181], v[40:41], v[136:137], v[180:181]
	v_pk_fma_f32 v[182:183], v[42:43], v[138:139], v[182:183]
	global_store_dwordx4 v[218:219], v[168:171], off
	global_store_dwordx4 v[218:219], v[172:175], off offset:64
	global_store_dwordx4 v[218:219], v[176:179], off offset:512
	global_store_dwordx4 v[218:219], v[180:183], off offset:576
	v_cvt_pk_bf16_f32 v52, v168, v169
	v_cvt_pk_bf16_f32 v53, v170, v171
	v_cvt_pk_bf16_f32 v48, v172, v173
	v_cvt_pk_bf16_f32 v49, v174, v175
	v_cvt_pk_bf16_f32 v44, v176, v177
	v_cvt_pk_bf16_f32 v45, v178, v179
	v_cvt_pk_bf16_f32 v40, v180, v181
	v_cvt_pk_bf16_f32 v41, v182, v183
	global_store_dwordx2 v[242:243], v[52:53], off
	global_store_dwordx2 v[242:243], v[48:49], off offset:32
	global_store_dwordx2 v[242:243], v[44:45], off offset:256
	global_store_dwordx2 v[242:243], v[40:41], off offset:288
	s_mov_b32 s0, 0x10000
	s_mov_b32 s1, 0
	v_lshl_add_u64 v[218:219], v[218:219], 0, s[0:1]
	s_mov_b32 s0, 0x8000
	s_mov_b32 s1, 0
	v_lshl_add_u64 v[242:243], v[242:243], 0, s[0:1]
	ds_bpermute_b32 v36, v198, v36
	ds_bpermute_b32 v37, v198, v37
	ds_bpermute_b32 v38, v198, v38
	ds_bpermute_b32 v39, v198, v39
	ds_bpermute_b32 v32, v198, v32
	ds_bpermute_b32 v33, v198, v33
	ds_bpermute_b32 v34, v198, v34
	ds_bpermute_b32 v35, v198, v35
	ds_bpermute_b32 v28, v198, v28
	ds_bpermute_b32 v29, v198, v29
	ds_bpermute_b32 v30, v198, v30
	ds_bpermute_b32 v31, v198, v31
	ds_bpermute_b32 v24, v198, v24
	ds_bpermute_b32 v25, v198, v25
	ds_bpermute_b32 v26, v198, v26
	ds_bpermute_b32 v27, v198, v27
	s_waitcnt vmcnt(36)
; __device__ __forceinline__ unsigned pk2(float lo, float hi) { const f32v2_t f = {lo, hi}; const bf16v2_t b = __builtin_convertvector(f, bf16v2_t); return __builtin_bit_cast(unsigned, b); }
;     __device__ __forceinline__ void operator()(const f32x4 (&acc)[2][2][4][2], const int upm, const int upn, const int usplit, int wr, int wc, int fr, int fq) const {
;     ...
;         const bool lat = upm * BM < NLAT; const int b = lat ? ((upm * BM) >> 11) : 16;
;         const float* gp = gate + (size_t)b * 6144 + col0;
;         f32x4 gv[2][2];
; #pragma unroll
;         for (int bj = 0; bj < 2; ++bj)
; #pragma unroll
;             for (int n = 0; n < 2; ++n) gv[bj][n] = *(const f32x4*)(gp + bj * HALF + n * 16);
;         const float* sb = lat ? src_lat : src_ctx - (size_t)NLAT * DM; float* db = lat ? dst_lat : dst_ctx - (size_t)NLAT * DM;
; #pragma unroll
;         for (int ai = 0; ai < 2; ++ai)
; #pragma unroll
;             for (int mh = 0; mh < 2; ++mh) {
;                 f32x4 xv[2][2][2];
; #pragma unroll
;                 for (int m = 0; m < 2; ++m)
; #pragma unroll
;                     for (int bj = 0; bj < 2; ++bj)
; #pragma unroll
;                         for (int n = 0; n < 2; ++n) xv[m][bj][n] = *(const f32x4*)(sb + (size_t)(row0 + ai * HALF + (mh * 2 + m) * 16) * DM + col0 + bj * HALF + n * 16);
;                 __builtin_amdgcn_sched_barrier(0);
; #pragma unroll
;                 for (int m = 0; m < 2; ++m)
; #pragma unroll
;                     for (int bj = 0; bj < 2; ++bj)
; #pragma unroll
;                         for (int n = 0; n < 2; ++n) {
;                             const size_t o = (size_t)(row0 + ai * HALF + (mh * 2 + m) * 16) * DM + col0 + bj * HALF + n * 16;
;                             const f32x4 r = xv[m][bj][n] + gv[bj][n] * acc[ai][bj][mh * 2 + m][n];
;                             *(f32x4*)(db + o) = r;
;                             if (xb && lat) { u32x2 pk; pk.x = pk2(r[0], r[1]); pk.y = pk2(r[2], r[3]); *(u32x2*)(xb + o) = pk; }
;                         }
	s_waitcnt lgkmcnt(0)
	v_pk_fma_f32 v[116:117], v[36:37], v[148:149], v[116:117]
	v_pk_fma_f32 v[118:119], v[38:39], v[150:151], v[118:119]
	v_pk_fma_f32 v[112:113], v[32:33], v[144:145], v[112:113]
	v_pk_fma_f32 v[114:115], v[34:35], v[146:147], v[114:115]
	v_pk_fma_f32 v[108:109], v[28:29], v[140:141], v[108:109]
	v_pk_fma_f32 v[110:111], v[30:31], v[142:143], v[110:111]
	v_pk_fma_f32 v[104:105], v[24:25], v[136:137], v[104:105]
	v_pk_fma_f32 v[106:107], v[26:27], v[138:139], v[106:107]
	global_store_dwordx4 v[218:219], v[116:119], off
	global_store_dwordx4 v[218:219], v[112:115], off offset:64
	global_store_dwordx4 v[218:219], v[108:111], off offset:512
	global_store_dwordx4 v[218:219], v[104:107], off offset:576
	v_cvt_pk_bf16_f32 v36, v116, v117
	v_cvt_pk_bf16_f32 v37, v118, v119
	v_cvt_pk_bf16_f32 v32, v112, v113
	v_cvt_pk_bf16_f32 v33, v114, v115
	v_cvt_pk_bf16_f32 v28, v108, v109
	v_cvt_pk_bf16_f32 v29, v110, v111
	v_cvt_pk_bf16_f32 v24, v104, v105
	v_cvt_pk_bf16_f32 v25, v106, v107
	global_store_dwordx2 v[242:243], v[36:37], off
	global_store_dwordx2 v[242:243], v[32:33], off offset:32
	global_store_dwordx2 v[242:243], v[28:29], off offset:256
	global_store_dwordx2 v[242:243], v[24:25], off offset:288
	s_mov_b32 s0, 0x10000
	s_mov_b32 s1, 0
	v_lshl_add_u64 v[218:219], v[218:219], 0, s[0:1]
	s_mov_b32 s0, 0x8000
	s_mov_b32 s1, 0
	v_lshl_add_u64 v[242:243], v[242:243], 0, s[0:1]
	ds_bpermute_b32 v20, v198, v20
	ds_bpermute_b32 v21, v198, v21
	ds_bpermute_b32 v22, v198, v22
	ds_bpermute_b32 v23, v198, v23
	ds_bpermute_b32 v16, v198, v16
	ds_bpermute_b32 v17, v198, v17
	ds_bpermute_b32 v18, v198, v18
	ds_bpermute_b32 v19, v198, v19
	ds_bpermute_b32 v12, v198, v12
	ds_bpermute_b32 v13, v198, v13
	ds_bpermute_b32 v14, v198, v14
	ds_bpermute_b32 v15, v198, v15
	ds_bpermute_b32 v8, v198, v8
	ds_bpermute_b32 v9, v198, v9
	ds_bpermute_b32 v10, v198, v10
	ds_bpermute_b32 v11, v198, v11
	s_waitcnt vmcnt(32)
	s_waitcnt lgkmcnt(0)
	v_pk_fma_f32 v[190:191], v[20:21], v[148:149], v[190:191]
	v_pk_fma_f32 v[192:193], v[22:23], v[150:151], v[192:193]
	v_pk_fma_f32 v[194:195], v[16:17], v[144:145], v[194:195]
	v_pk_fma_f32 v[196:197], v[18:19], v[146:147], v[196:197]
	v_pk_fma_f32 v[234:235], v[12:13], v[140:141], v[234:235]
	v_pk_fma_f32 v[236:237], v[14:15], v[142:143], v[236:237]
	v_pk_fma_f32 v[238:239], v[8:9], v[136:137], v[238:239]
	v_pk_fma_f32 v[240:241], v[10:11], v[138:139], v[240:241]
	global_store_dwordx4 v[218:219], v[190:193], off
	global_store_dwordx4 v[218:219], v[194:197], off offset:64
	global_store_dwordx4 v[218:219], v[234:237], off offset:512
	global_store_dwordx4 v[218:219], v[238:241], off offset:576
	v_cvt_pk_bf16_f32 v20, v190, v191
	v_cvt_pk_bf16_f32 v21, v192, v193
	v_cvt_pk_bf16_f32 v16, v194, v195
	v_cvt_pk_bf16_f32 v17, v196, v197
	v_cvt_pk_bf16_f32 v12, v234, v235
	v_cvt_pk_bf16_f32 v13, v236, v237
	v_cvt_pk_bf16_f32 v8, v238, v239
	v_cvt_pk_bf16_f32 v9, v240, v241
	global_store_dwordx2 v[242:243], v[20:21], off
	global_store_dwordx2 v[242:243], v[16:17], off offset:32
	global_store_dwordx2 v[242:243], v[12:13], off offset:256
	global_store_dwordx2 v[242:243], v[8:9], off offset:288
	s_branch .LBB0_1846
.Lmy_epi_p7_nobf:
	ds_bpermute_b32 v132, v198, v132
	ds_bpermute_b32 v133, v198, v133
	ds_bpermute_b32 v134, v198, v134
	ds_bpermute_b32 v135, v198, v135
	ds_bpermute_b32 v128, v198, v128
	ds_bpermute_b32 v129, v198, v129
	ds_bpermute_b32 v130, v198, v130
	ds_bpermute_b32 v131, v198, v131
	ds_bpermute_b32 v124, v198, v124
	ds_bpermute_b32 v125, v198, v125
	ds_bpermute_b32 v126, v198, v126
	ds_bpermute_b32 v127, v198, v127
	ds_bpermute_b32 v120, v198, v120
	ds_bpermute_b32 v121, v198, v121
	ds_bpermute_b32 v122, v198, v122
	ds_bpermute_b32 v123, v198, v123
	s_waitcnt vmcnt(8)
	s_waitcnt lgkmcnt(0)
	v_pk_fma_f32 v[152:153], v[132:133], v[148:149], v[152:153]
	v_pk_fma_f32 v[154:155], v[134:135], v[150:151], v[154:155]
	v_pk_fma_f32 v[156:157], v[128:129], v[144:145], v[156:157]
	v_pk_fma_f32 v[158:159], v[130:131], v[146:147], v[158:159]
	v_pk_fma_f32 v[160:161], v[124:125], v[140:141], v[160:161]
	v_pk_fma_f32 v[162:163], v[126:127], v[142:143], v[162:163]
	v_pk_fma_f32 v[164:165], v[120:121], v[136:137], v[164:165]
	v_pk_fma_f32 v[166:167], v[122:123], v[138:139], v[166:167]
	global_store_dwordx4 v[218:219], v[152:155], off
	global_store_dwordx4 v[218:219], v[156:159], off offset:64
	global_store_dwordx4 v[218:219], v[160:163], off offset:512
	global_store_dwordx4 v[218:219], v[164:167], off offset:576
	s_mov_b32 s0, 0x10000
	s_mov_b32 s1, 0
	v_lshl_add_u64 v[218:219], v[218:219], 0, s[0:1]
	global_load_dwordx4 v[152:155], v[200:201], off
	global_load_dwordx4 v[156:159], v[200:201], off offset:64
	global_load_dwordx4 v[160:163], v[200:201], off offset:512
	global_load_dwordx4 v[164:167], v[200:201], off offset:576
	s_mov_b32 s0, 0x50000
	s_mov_b32 s1, 0
	v_lshl_add_u64 v[200:201], v[200:201], 0, s[0:1]
	global_load_dwordx4 v[132:135], v[200:201], off
	global_load_dwordx4 v[128:131], v[200:201], off offset:64
	global_load_dwordx4 v[124:127], v[200:201], off offset:512
	global_load_dwordx4 v[120:123], v[200:201], off offset:576
	s_mov_b32 s0, 0x10000
	s_mov_b32 s1, 0
	v_lshl_add_u64 v[200:201], v[200:201], 0, s[0:1]
	ds_bpermute_b32 v116, v198, v116
	ds_bpermute_b32 v117, v198, v117
	ds_bpermute_b32 v118, v198, v118
	ds_bpermute_b32 v119, v198, v119
	ds_bpermute_b32 v112, v198, v112
	ds_bpermute_b32 v113, v198, v113
	ds_bpermute_b32 v114, v198, v114
	ds_bpermute_b32 v115, v198, v115
	ds_bpermute_b32 v108, v198, v108
	ds_bpermute_b32 v109, v198, v109
	ds_bpermute_b32 v110, v198, v110
	ds_bpermute_b32 v111, v198, v111
	ds_bpermute_b32 v104, v198, v104
	ds_bpermute_b32 v105, v198, v105
	ds_bpermute_b32 v106, v198, v106
	ds_bpermute_b32 v107, v198, v107
	s_waitcnt vmcnt(16)
; __device__ __forceinline__ unsigned pk2(float lo, float hi) { const f32v2_t f = {lo, hi}; const bf16v2_t b = __builtin_convertvector(f, bf16v2_t); return __builtin_bit_cast(unsigned, b); }
;     __device__ __forceinline__ void operator()(const f32x4 (&acc)[2][2][4][2], const int upm, const int upn, const int usplit, int wr, int wc, int fr, int fq) const {
;     ...
;         const bool lat = upm * BM < NLAT; const int b = lat ? ((upm * BM) >> 11) : 16;
;         const float* gp = gate + (size_t)b * 6144 + col0;
;         f32x4 gv[2][2];
; #pragma unroll
;         for (int bj = 0; bj < 2; ++bj)
; #pragma unroll
;             for (int n = 0; n < 2; ++n) gv[bj][n] = *(const f32x4*)(gp + bj * HALF + n * 16);
;         const float* sb = lat ? src_lat : src_ctx - (size_t)NLAT * DM; float* db = lat ? dst_lat : dst_ctx - (size_t)NLAT * DM;
; #pragma unroll
;         for (int ai = 0; ai < 2; ++ai)
; #pragma unroll
;             for (int mh = 0; mh < 2; ++mh) {
;                 f32x4 xv[2][2][2];
; #pragma unroll
;                 for (int m = 0; m < 2; ++m)
; #pragma unroll
;                     for (int bj = 0; bj < 2; ++bj)
; #pragma unroll
;                         for (int n = 0; n < 2; ++n) xv[m][bj][n] = *(const f32x4*)(sb + (size_t)(row0 + ai * HALF + (mh * 2 + m) * 16) * DM + col0 + bj * HALF + n * 16);
;                 __builtin_amdgcn_sched_barrier(0);
; #pragma unroll
;                 for (int m = 0; m < 2; ++m)
; #pragma unroll
;                     for (int bj = 0; bj < 2; ++bj)
; #pragma unroll
;                         for (int n = 0; n < 2; ++n) {
;                             const size_t o = (size_t)(row0 + ai * HALF + (mh * 2 + m) * 16) * DM + col0 + bj * HALF + n * 16;
;                             const f32x4 r = xv[m][bj][n] + gv[bj][n] * acc[ai][bj][mh * 2 + m][n];
;                             *(f32x4*)(db + o) = r;
;                             if (xb && lat) { u32x2 pk; pk.x = pk2(r[0], r[1]); pk.y = pk2(r[2], r[3]); *(u32x2*)(xb + o) = pk; }
;                         }
	s_waitcnt lgkmcnt(0)
	v_pk_fma_f32 v[168:169], v[116:117], v[148:149], v[168:169]
	v_pk_fma_f32 v[170:171], v[118:119], v[150:151], v[170:171]
	v_pk_fma_f32 v[172:173], v[112:113], v[144:145], v[172:173]
	v_pk_fma_f32 v[174:175], v[114:115], v[146:147], v[174:175]
	v_pk_fma_f32 v[176:177], v[108:109], v[140:141], v[176:177]
	v_pk_fma_f32 v[178:179], v[110:111], v[142:143], v[178:179]
	v_pk_fma_f32 v[180:181], v[104:105], v[136:137], v[180:181]
	v_pk_fma_f32 v[182:183], v[106:107], v[138:139], v[182:183]
	global_store_dwordx4 v[218:219], v[168:171], off
	global_store_dwordx4 v[218:219], v[172:175], off offset:64
	global_store_dwordx4 v[218:219], v[176:179], off offset:512
	global_store_dwordx4 v[218:219], v[180:183], off offset:576
	s_mov_b32 s0, 0x10000
	s_mov_b32 s1, 0
	v_lshl_add_u64 v[218:219], v[218:219], 0, s[0:1]
	global_load_dwordx4 v[168:171], v[200:201], off
	global_load_dwordx4 v[172:175], v[200:201], off offset:64
	global_load_dwordx4 v[176:179], v[200:201], off offset:512
	global_load_dwordx4 v[180:183], v[200:201], off offset:576
	s_mov_b32 s0, 0x10000
	s_mov_b32 s1, 0
	v_lshl_add_u64 v[200:201], v[200:201], 0, s[0:1]
	global_load_dwordx4 v[116:119], v[200:201], off
	global_load_dwordx4 v[112:115], v[200:201], off offset:64
	global_load_dwordx4 v[108:111], v[200:201], off offset:512
	global_load_dwordx4 v[104:107], v[200:201], off offset:576
	s_mov_b32 s0, 0x10000
	s_mov_b32 s1, 0
	v_lshl_add_u64 v[200:201], v[200:201], 0, s[0:1]
	ds_bpermute_b32 v100, v198, v100
	ds_bpermute_b32 v101, v198, v101
	ds_bpermute_b32 v102, v198, v102
	ds_bpermute_b32 v103, v198, v103
	ds_bpermute_b32 v96, v198, v96
	ds_bpermute_b32 v97, v198, v97
	ds_bpermute_b32 v98, v198, v98
	ds_bpermute_b32 v99, v198, v99
	ds_bpermute_b32 v92, v198, v92
	ds_bpermute_b32 v93, v198, v93
	ds_bpermute_b32 v94, v198, v94
	ds_bpermute_b32 v95, v198, v95
	ds_bpermute_b32 v88, v198, v88
	ds_bpermute_b32 v89, v198, v89
	ds_bpermute_b32 v90, v198, v90
	ds_bpermute_b32 v91, v198, v91
	s_waitcnt vmcnt(24)
	s_waitcnt lgkmcnt(0)
	v_pk_fma_f32 v[190:191], v[100:101], v[148:149], v[190:191]
	v_pk_fma_f32 v[192:193], v[102:103], v[150:151], v[192:193]
	v_pk_fma_f32 v[194:195], v[96:97], v[144:145], v[194:195]
	v_pk_fma_f32 v[196:197], v[98:99], v[146:147], v[196:197]
	v_pk_fma_f32 v[234:235], v[92:93], v[140:141], v[234:235]
	v_pk_fma_f32 v[236:237], v[94:95], v[142:143], v[236:237]
	v_pk_fma_f32 v[238:239], v[88:89], v[136:137], v[238:239]
	v_pk_fma_f32 v[240:241], v[90:91], v[138:139], v[240:241]
	global_store_dwordx4 v[218:219], v[190:193], off
	global_store_dwordx4 v[218:219], v[194:197], off offset:64
	global_store_dwordx4 v[218:219], v[234:237], off offset:512
	global_store_dwordx4 v[218:219], v[238:241], off offset:576
	s_mov_b32 s0, 0x10000
	s_mov_b32 s1, 0
	v_lshl_add_u64 v[218:219], v[218:219], 0, s[0:1]
	global_load_dwordx4 v[190:193], v[200:201], off
	global_load_dwordx4 v[194:197], v[200:201], off offset:64
	global_load_dwordx4 v[234:237], v[200:201], off offset:512
	global_load_dwordx4 v[238:241], v[200:201], off offset:576
	ds_bpermute_b32 v84, v198, v84
	ds_bpermute_b32 v85, v198, v85
	ds_bpermute_b32 v86, v198, v86
	ds_bpermute_b32 v87, v198, v87
	ds_bpermute_b32 v80, v198, v80
	ds_bpermute_b32 v81, v198, v81
	ds_bpermute_b32 v82, v198, v82
	ds_bpermute_b32 v83, v198, v83
	ds_bpermute_b32 v76, v198, v76
	ds_bpermute_b32 v77, v198, v77
	ds_bpermute_b32 v78, v198, v78
	ds_bpermute_b32 v79, v198, v79
	ds_bpermute_b32 v72, v198, v72
	ds_bpermute_b32 v73, v198, v73
	ds_bpermute_b32 v74, v198, v74
	ds_bpermute_b32 v75, v198, v75
	s_waitcnt vmcnt(24)
	s_waitcnt lgkmcnt(0)
	v_pk_fma_f32 v[152:153], v[84:85], v[148:149], v[152:153]
	v_pk_fma_f32 v[154:155], v[86:87], v[150:151], v[154:155]
	v_pk_fma_f32 v[156:157], v[80:81], v[144:145], v[156:157]
	v_pk_fma_f32 v[158:159], v[82:83], v[146:147], v[158:159]
	v_pk_fma_f32 v[160:161], v[76:77], v[140:141], v[160:161]
	v_pk_fma_f32 v[162:163], v[78:79], v[142:143], v[162:163]
	v_pk_fma_f32 v[164:165], v[72:73], v[136:137], v[164:165]
	v_pk_fma_f32 v[166:167], v[74:75], v[138:139], v[166:167]
	global_store_dwordx4 v[218:219], v[152:155], off
	global_store_dwordx4 v[218:219], v[156:159], off offset:64
	global_store_dwordx4 v[218:219], v[160:163], off offset:512
	global_store_dwordx4 v[218:219], v[164:167], off offset:576
	s_mov_b32 s0, 0x50000
	s_mov_b32 s1, 0
	v_lshl_add_u64 v[218:219], v[218:219], 0, s[0:1]
	ds_bpermute_b32 v68, v198, v68
	ds_bpermute_b32 v69, v198, v69
	ds_bpermute_b32 v70, v198, v70
	ds_bpermute_b32 v71, v198, v71
	ds_bpermute_b32 v64, v198, v64
	ds_bpermute_b32 v65, v198, v65
	ds_bpermute_b32 v66, v198, v66
	ds_bpermute_b32 v67, v198, v67
	ds_bpermute_b32 v60, v198, v60
	ds_bpermute_b32 v61, v198, v61
	ds_bpermute_b32 v62, v198, v62
	ds_bpermute_b32 v63, v198, v63
	ds_bpermute_b32 v56, v198, v56
	ds_bpermute_b32 v57, v198, v57
	ds_bpermute_b32 v58, v198, v58
	ds_bpermute_b32 v59, v198, v59
	s_waitcnt vmcnt(24)
; __device__ __forceinline__ unsigned pk2(float lo, float hi) { const f32v2_t f = {lo, hi}; const bf16v2_t b = __builtin_convertvector(f, bf16v2_t); return __builtin_bit_cast(unsigned, b); }
;     __device__ __forceinline__ void operator()(const f32x4 (&acc)[2][2][4][2], const int upm, const int upn, const int usplit, int wr, int wc, int fr, int fq) const {
;     ...
;         const bool lat = upm * BM < NLAT; const int b = lat ? ((upm * BM) >> 11) : 16;
;         const float* gp = gate + (size_t)b * 6144 + col0;
;         f32x4 gv[2][2];
; #pragma unroll
;         for (int bj = 0; bj < 2; ++bj)
; #pragma unroll
;             for (int n = 0; n < 2; ++n) gv[bj][n] = *(const f32x4*)(gp + bj * HALF + n * 16);
;         const float* sb = lat ? src_lat : src_ctx - (size_t)NLAT * DM; float* db = lat ? dst_lat : dst_ctx - (size_t)NLAT * DM;
; #pragma unroll
;         for (int ai = 0; ai < 2; ++ai)
; #pragma unroll
;             for (int mh = 0; mh < 2; ++mh) {
;                 f32x4 xv[2][2][2];
; #pragma unroll
;                 for (int m = 0; m < 2; ++m)
; #pragma unroll
;                     for (int bj = 0; bj < 2; ++bj)
; #pragma unroll
;                         for (int n = 0; n < 2; ++n) xv[m][bj][n] = *(const f32x4*)(sb + (size_t)(row0 + ai * HALF + (mh * 2 + m) * 16) * DM + col0 + bj * HALF + n * 16);
;                 __builtin_amdgcn_sched_barrier(0);
; #pragma unroll
;                 for (int m = 0; m < 2; ++m)
; #pragma unroll
;                     for (int bj = 0; bj < 2; ++bj)
; #pragma unroll
;                         for (int n = 0; n < 2; ++n) {
;                             const size_t o = (size_t)(row0 + ai * HALF + (mh * 2 + m) * 16) * DM + col0 + bj * HALF + n * 16;
;                             const f32x4 r = xv[m][bj][n] + gv[bj][n] * acc[ai][bj][mh * 2 + m][n];
;                             *(f32x4*)(db + o) = r;
;                             if (xb && lat) { u32x2 pk; pk.x = pk2(r[0], r[1]); pk.y = pk2(r[2], r[3]); *(u32x2*)(xb + o) = pk; }
;                         }
	s_waitcnt lgkmcnt(0)
	v_pk_fma_f32 v[132:133], v[68:69], v[148:149], v[132:133]
	v_pk_fma_f32 v[134:135], v[70:71], v[150:151], v[134:135]
	v_pk_fma_f32 v[128:129], v[64:65], v[144:145], v[128:129]
	v_pk_fma_f32 v[130:131], v[66:67], v[146:147], v[130:131]
	v_pk_fma_f32 v[124:125], v[60:61], v[140:141], v[124:125]
	v_pk_fma_f32 v[126:127], v[62:63], v[142:143], v[126:127]
	v_pk_fma_f32 v[120:121], v[56:57], v[136:137], v[120:121]
	v_pk_fma_f32 v[122:123], v[58:59], v[138:139], v[122:123]
	global_store_dwordx4 v[218:219], v[132:135], off
	global_store_dwordx4 v[218:219], v[128:131], off offset:64
	global_store_dwordx4 v[218:219], v[124:127], off offset:512
	global_store_dwordx4 v[218:219], v[120:123], off offset:576
	s_mov_b32 s0, 0x10000
	s_mov_b32 s1, 0
	v_lshl_add_u64 v[218:219], v[218:219], 0, s[0:1]
	ds_bpermute_b32 v52, v198, v52
	ds_bpermute_b32 v53, v198, v53
	ds_bpermute_b32 v54, v198, v54
	ds_bpermute_b32 v55, v198, v55
	ds_bpermute_b32 v48, v198, v48
	ds_bpermute_b32 v49, v198, v49
	ds_bpermute_b32 v50, v198, v50
	ds_bpermute_b32 v51, v198, v51
	ds_bpermute_b32 v44, v198, v44
	ds_bpermute_b32 v45, v198, v45
	ds_bpermute_b32 v46, v198, v46
	ds_bpermute_b32 v47, v198, v47
	ds_bpermute_b32 v40, v198, v40
	ds_bpermute_b32 v41, v198, v41
	ds_bpermute_b32 v42, v198, v42
	ds_bpermute_b32 v43, v198, v43
	s_waitcnt vmcnt(20)
	s_waitcnt lgkmcnt(0)
	v_pk_fma_f32 v[168:169], v[52:53], v[148:149], v[168:169]
	v_pk_fma_f32 v[170:171], v[54:55], v[150:151], v[170:171]
	v_pk_fma_f32 v[172:173], v[48:49], v[144:145], v[172:173]
	v_pk_fma_f32 v[174:175], v[50:51], v[146:147], v[174:175]
	v_pk_fma_f32 v[176:177], v[44:45], v[140:141], v[176:177]
	v_pk_fma_f32 v[178:179], v[46:47], v[142:143], v[178:179]
	v_pk_fma_f32 v[180:181], v[40:41], v[136:137], v[180:181]
	v_pk_fma_f32 v[182:183], v[42:43], v[138:139], v[182:183]
	global_store_dwordx4 v[218:219], v[168:171], off
	global_store_dwordx4 v[218:219], v[172:175], off offset:64
	global_store_dwordx4 v[218:219], v[176:179], off offset:512
	global_store_dwordx4 v[218:219], v[180:183], off offset:576
	s_mov_b32 s0, 0x10000
	s_mov_b32 s1, 0
	v_lshl_add_u64 v[218:219], v[218:219], 0, s[0:1]
	ds_bpermute_b32 v36, v198, v36
	ds_bpermute_b32 v37, v198, v37
	ds_bpermute_b32 v38, v198, v38
	ds_bpermute_b32 v39, v198, v39
	ds_bpermute_b32 v32, v198, v32
	ds_bpermute_b32 v33, v198, v33
	ds_bpermute_b32 v34, v198, v34
	ds_bpermute_b32 v35, v198, v35
	ds_bpermute_b32 v28, v198, v28
	ds_bpermute_b32 v29, v198, v29
	ds_bpermute_b32 v30, v198, v30
	ds_bpermute_b32 v31, v198, v31
	ds_bpermute_b32 v24, v198, v24
	ds_bpermute_b32 v25, v198, v25
	ds_bpermute_b32 v26, v198, v26
	ds_bpermute_b32 v27, v198, v27
	s_waitcnt vmcnt(20)
	s_waitcnt lgkmcnt(0)
	v_pk_fma_f32 v[116:117], v[36:37], v[148:149], v[116:117]
	v_pk_fma_f32 v[118:119], v[38:39], v[150:151], v[118:119]
	v_pk_fma_f32 v[112:113], v[32:33], v[144:145], v[112:113]
	v_pk_fma_f32 v[114:115], v[34:35], v[146:147], v[114:115]
	v_pk_fma_f32 v[108:109], v[28:29], v[140:141], v[108:109]
	v_pk_fma_f32 v[110:111], v[30:31], v[142:143], v[110:111]
	v_pk_fma_f32 v[104:105], v[24:25], v[136:137], v[104:105]
	v_pk_fma_f32 v[106:107], v[26:27], v[138:139], v[106:107]
	global_store_dwordx4 v[218:219], v[116:119], off
	global_store_dwordx4 v[218:219], v[112:115], off offset:64
	global_store_dwordx4 v[218:219], v[108:111], off offset:512
	global_store_dwordx4 v[218:219], v[104:107], off offset:576
	s_mov_b32 s0, 0x10000
	s_mov_b32 s1, 0
	v_lshl_add_u64 v[218:219], v[218:219], 0, s[0:1]
	ds_bpermute_b32 v20, v198, v20
	ds_bpermute_b32 v21, v198, v21
	ds_bpermute_b32 v22, v198, v22
	ds_bpermute_b32 v23, v198, v23
	ds_bpermute_b32 v16, v198, v16
	ds_bpermute_b32 v17, v198, v17
	ds_bpermute_b32 v18, v198, v18
	ds_bpermute_b32 v19, v198, v19
	ds_bpermute_b32 v12, v198, v12
	ds_bpermute_b32 v13, v198, v13
	ds_bpermute_b32 v14, v198, v14
	ds_bpermute_b32 v15, v198, v15
	ds_bpermute_b32 v8, v198, v8
	ds_bpermute_b32 v9, v198, v9
	ds_bpermute_b32 v10, v198, v10
	ds_bpermute_b32 v11, v198, v11
	s_waitcnt vmcnt(16)
	s_waitcnt lgkmcnt(0)
	v_pk_fma_f32 v[190:191], v[20:21], v[148:149], v[190:191]
	v_pk_fma_f32 v[192:193], v[22:23], v[150:151], v[192:193]
	v_pk_fma_f32 v[194:195], v[16:17], v[144:145], v[194:195]
	v_pk_fma_f32 v[196:197], v[18:19], v[146:147], v[196:197]
	v_pk_fma_f32 v[234:235], v[12:13], v[140:141], v[234:235]
	v_pk_fma_f32 v[236:237], v[14:15], v[142:143], v[236:237]
	v_pk_fma_f32 v[238:239], v[8:9], v[136:137], v[238:239]
	v_pk_fma_f32 v[240:241], v[10:11], v[138:139], v[240:241]
	global_store_dwordx4 v[218:219], v[190:193], off
	global_store_dwordx4 v[218:219], v[194:197], off offset:64
	global_store_dwordx4 v[218:219], v[234:237], off offset:512
	global_store_dwordx4 v[218:219], v[238:241], off offset:576
	s_branch .LBB0_1846
